# phase 0 adaLN K loop rewritten: weight column loads 32 rows per batch with two batches in flight, LDS broadcast reads double-buffered
# speedup vs baseline: 1.0019x; 1.0019x over previous
; __device__ __forceinline__ void phase0(const Params& p, unsigned char* smem) {
;     ...
;             const int kg = tid >> 6, col = tid & 63;
;             float acc[9];
; #pragma unroll
;             for (int v = 0; v < 9; ++v) acc[v] = 0.f;
;             const float* wp = p.ada_w + ((size_t)l * 1024 + kg * 128) * 3072 + n0 + col;
; #pragma unroll 2
;             for (int kk = 0; kk < 128; kk += 4) {
;                 const float w0 = wp[(size_t)(kk + 0) * 3072], w1 = wp[(size_t)(kk + 1) * 3072], w2 = wp[(size_t)(kk + 2) * 3072], w3 = wp[(size_t)(kk + 3) * 3072];
; #pragma unroll
;                 for (int v = 0; v < 9; ++v) {
;                     const float4 sv = *(const float4*)(ssc + v * 1024 + kg * 128 + kk);
;                     acc[v] += sv.x * w0 + sv.y * w1 + sv.z * w2 + sv.w * w3;
;                 }
;             }
.LBB0_30:
	s_or_b64 exec, exec, s[42:43]
	s_mul_hi_i32 s20, s59, 0x2aaaaaab
	s_lshr_b32 s21, s20, 31
	s_ashr_i32 s20, s20, 3
	s_add_i32 s26, s20, s21
	s_mul_i32 s20, s26, 48
	s_sub_i32 s20, s59, s20
	s_lshl_b32 s24, s20, 6
	s_ashr_i32 s25, s24, 31
	s_mul_i32 s23, s26, 0xc00000
	s_lshl_b64 s[20:21], s[24:25], 2
	s_mul_hi_i32 s22, s26, 0xc00000
	s_add_u32 s20, s23, s20
	s_addc_u32 s21, s22, s21
	v_mov_b32_e32 v104, 0
	v_lshl_add_u64 v[102:103], v[78:79], 0, s[20:21]
	s_mov_b32 s42, -4
	v_mov_b32_e32 v81, v119
	v_mov_b32_e32 v105, v104
	v_mov_b32_e32 v106, v104
	v_mov_b32_e32 v107, v104
	v_mov_b32_e32 v108, v104
	v_mov_b32_e32 v109, v104
	v_mov_b32_e32 v110, v104
	v_mov_b32_e32 v111, v104
	v_mov_b32_e32 v83, v104
	s_waitcnt lgkmcnt(0)
	s_barrier
	v_readfirstlane_b32 s76, v102
	v_readfirstlane_b32 s77, v103
	v_and_b32_e32 v40, 63, v234
	v_lshlrev_b32_e32 v40, 2, v40
	s_nop 1
	s_sub_u32 s78, s76, 0x15000
	s_subb_u32 s79, s77, 0
	global_load_dword v142, v40, s[78:79]
	s_add_u32 s78, s78, 0x3000
	s_addc_u32 s79, s79, 0
	global_load_dword v143, v40, s[78:79]
	s_add_u32 s78, s78, 0x3000
	s_addc_u32 s79, s79, 0
	global_load_dword v144, v40, s[78:79]
	s_add_u32 s78, s78, 0x3000
	s_addc_u32 s79, s79, 0
	global_load_dword v145, v40, s[78:79]
	s_add_u32 s78, s78, 0x3000
	s_addc_u32 s79, s79, 0
	global_load_dword v146, v40, s[78:79]
	s_add_u32 s78, s78, 0x3000
	s_addc_u32 s79, s79, 0
	global_load_dword v147, v40, s[78:79]
	s_add_u32 s78, s78, 0x3000
	s_addc_u32 s79, s79, 0
	global_load_dword v148, v40, s[78:79]
	s_add_u32 s78, s78, 0x3000
	s_addc_u32 s79, s79, 0
	global_load_dword v149, v40, s[78:79]
	s_add_u32 s78, s78, 0x3000
	s_addc_u32 s79, s79, 0
	global_load_dword v150, v40, s[78:79]
	s_add_u32 s78, s78, 0x3000
	s_addc_u32 s79, s79, 0
	global_load_dword v151, v40, s[78:79]
	s_add_u32 s78, s78, 0x3000
	s_addc_u32 s79, s79, 0
	global_load_dword v152, v40, s[78:79]
	s_add_u32 s78, s78, 0x3000
	s_addc_u32 s79, s79, 0
	global_load_dword v153, v40, s[78:79]
	s_add_u32 s78, s78, 0x3000
	s_addc_u32 s79, s79, 0
	global_load_dword v154, v40, s[78:79]
	s_add_u32 s78, s78, 0x3000
	s_addc_u32 s79, s79, 0
	global_load_dword v155, v40, s[78:79]
	s_add_u32 s78, s78, 0x3000
	s_addc_u32 s79, s79, 0
	global_load_dword v156, v40, s[78:79]
	s_add_u32 s78, s78, 0x3000
	s_addc_u32 s79, s79, 0
	global_load_dword v157, v40, s[78:79]
	s_add_u32 s78, s78, 0x3000
	s_addc_u32 s79, s79, 0
	global_load_dword v158, v40, s[78:79]
	s_add_u32 s78, s78, 0x3000
	s_addc_u32 s79, s79, 0
	global_load_dword v159, v40, s[78:79]
	s_add_u32 s78, s78, 0x3000
	s_addc_u32 s79, s79, 0
	global_load_dword v160, v40, s[78:79]
	s_add_u32 s78, s78, 0x3000
	s_addc_u32 s79, s79, 0
	global_load_dword v161, v40, s[78:79]
	s_add_u32 s78, s78, 0x3000
	s_addc_u32 s79, s79, 0
	global_load_dword v162, v40, s[78:79]
	s_add_u32 s78, s78, 0x3000
	s_addc_u32 s79, s79, 0
	global_load_dword v163, v40, s[78:79]
	s_add_u32 s78, s78, 0x3000
	s_addc_u32 s79, s79, 0
	global_load_dword v164, v40, s[78:79]
	s_add_u32 s78, s78, 0x3000
	s_addc_u32 s79, s79, 0
	global_load_dword v165, v40, s[78:79]
	s_add_u32 s78, s78, 0x3000
	s_addc_u32 s79, s79, 0
	global_load_dword v166, v40, s[78:79]
	s_add_u32 s78, s78, 0x3000
	s_addc_u32 s79, s79, 0
	global_load_dword v167, v40, s[78:79]
	s_add_u32 s78, s78, 0x3000
	s_addc_u32 s79, s79, 0
	global_load_dword v168, v40, s[78:79]
	s_add_u32 s78, s78, 0x3000
	s_addc_u32 s79, s79, 0
	global_load_dword v169, v40, s[78:79]
	s_add_u32 s78, s78, 0x3000
	s_addc_u32 s79, s79, 0
	global_load_dword v170, v40, s[78:79]
	s_add_u32 s78, s78, 0x3000
	s_addc_u32 s79, s79, 0
	global_load_dword v171, v40, s[78:79]
	s_add_u32 s78, s78, 0x3000
	s_addc_u32 s79, s79, 0
	global_load_dword v172, v40, s[78:79]
	s_add_u32 s78, s78, 0x3000
	s_addc_u32 s79, s79, 0
	global_load_dword v173, v40, s[78:79]
	s_add_u32 s78, s78, 0x3000
	s_addc_u32 s79, s79, 0
	global_load_dword v174, v40, s[78:79]
	s_add_u32 s78, s78, 0x3000
	s_addc_u32 s79, s79, 0
	global_load_dword v175, v40, s[78:79]
	s_add_u32 s78, s78, 0x3000
	s_addc_u32 s79, s79, 0
	global_load_dword v176, v40, s[78:79]
	s_add_u32 s78, s78, 0x3000
	s_addc_u32 s79, s79, 0
	global_load_dword v177, v40, s[78:79]
	s_add_u32 s78, s78, 0x3000
	s_addc_u32 s79, s79, 0
	global_load_dword v178, v40, s[78:79]
	s_add_u32 s78, s78, 0x3000
	s_addc_u32 s79, s79, 0
	global_load_dword v179, v40, s[78:79]
	s_add_u32 s78, s78, 0x3000
	s_addc_u32 s79, s79, 0
	global_load_dword v180, v40, s[78:79]
	s_add_u32 s78, s78, 0x3000
	s_addc_u32 s79, s79, 0
	global_load_dword v181, v40, s[78:79]
	s_add_u32 s78, s78, 0x3000
	s_addc_u32 s79, s79, 0
	global_load_dword v182, v40, s[78:79]
	s_add_u32 s78, s78, 0x3000
	s_addc_u32 s79, s79, 0
	global_load_dword v183, v40, s[78:79]
	s_add_u32 s78, s78, 0x3000
	s_addc_u32 s79, s79, 0
	global_load_dword v184, v40, s[78:79]
	s_add_u32 s78, s78, 0x3000
	s_addc_u32 s79, s79, 0
	global_load_dword v185, v40, s[78:79]
	s_add_u32 s78, s78, 0x3000
	s_addc_u32 s79, s79, 0
	global_load_dword v186, v40, s[78:79]
	s_add_u32 s78, s78, 0x3000
	s_addc_u32 s79, s79, 0
	global_load_dword v187, v40, s[78:79]
	s_add_u32 s78, s78, 0x3000
	s_addc_u32 s79, s79, 0
	global_load_dword v188, v40, s[78:79]
	s_add_u32 s78, s78, 0x3000
	s_addc_u32 s79, s79, 0
	global_load_dword v189, v40, s[78:79]
	s_add_u32 s78, s78, 0x3000
	s_addc_u32 s79, s79, 0
	global_load_dword v190, v40, s[78:79]
	s_add_u32 s78, s78, 0x3000
	s_addc_u32 s79, s79, 0
	global_load_dword v191, v40, s[78:79]
	s_add_u32 s78, s78, 0x3000
	s_addc_u32 s79, s79, 0
	global_load_dword v192, v40, s[78:79]
	s_add_u32 s78, s78, 0x3000
	s_addc_u32 s79, s79, 0
	global_load_dword v193, v40, s[78:79]
	s_add_u32 s78, s78, 0x3000
; __device__ __forceinline__ void phase0(const Params& p, unsigned char* smem) {
;     ...
;             for (int kk = 0; kk < 128; kk += 4) {
;                 const float w0 = wp[(size_t)(kk + 0) * 3072], w1 = wp[(size_t)(kk + 1) * 3072], w2 = wp[(size_t)(kk + 2) * 3072], w3 = wp[(size_t)(kk + 3) * 3072];
; #pragma unroll
;                 for (int v = 0; v < 9; ++v) {
;                     const float4 sv = *(const float4*)(ssc + v * 1024 + kg * 128 + kk);
;                     acc[v] += sv.x * w0 + sv.y * w1 + sv.z * w2 + sv.w * w3;
;                 }
;             }
	s_addc_u32 s79, s79, 0
	global_load_dword v194, v40, s[78:79]
	s_add_u32 s78, s78, 0x3000
	s_addc_u32 s79, s79, 0
	global_load_dword v195, v40, s[78:79]
	s_add_u32 s78, s78, 0x3000
	s_addc_u32 s79, s79, 0
	global_load_dword v196, v40, s[78:79]
	s_add_u32 s78, s78, 0x3000
	s_addc_u32 s79, s79, 0
	global_load_dword v197, v40, s[78:79]
	s_add_u32 s78, s78, 0x3000
	s_addc_u32 s79, s79, 0
	global_load_dword v198, v40, s[78:79]
	s_add_u32 s78, s78, 0x3000
	s_addc_u32 s79, s79, 0
	global_load_dword v199, v40, s[78:79]
	s_add_u32 s78, s78, 0x3000
	s_addc_u32 s79, s79, 0
	global_load_dword v200, v40, s[78:79]
	s_add_u32 s78, s78, 0x3000
	s_addc_u32 s79, s79, 0
	global_load_dword v201, v40, s[78:79]
	s_add_u32 s78, s78, 0x3000
	s_addc_u32 s79, s79, 0
	global_load_dword v202, v40, s[78:79]
	s_add_u32 s78, s78, 0x3000
	s_addc_u32 s79, s79, 0
	global_load_dword v203, v40, s[78:79]
	s_add_u32 s78, s78, 0x3000
	s_addc_u32 s79, s79, 0
	global_load_dword v204, v40, s[78:79]
	s_add_u32 s78, s78, 0x3000
	s_addc_u32 s79, s79, 0
	global_load_dword v205, v40, s[78:79]
	s_add_u32 s78, s78, 0x3000
	s_addc_u32 s79, s79, 0
	ds_read_b128 v[4:7], v81
	ds_read_b128 v[8:11], v81 offset:4096
	ds_read_b128 v[12:15], v81 offset:8192
	ds_read_b128 v[16:19], v81 offset:12288
	ds_read_b128 v[20:23], v81 offset:16384
	ds_read_b128 v[24:27], v81 offset:20480
	ds_read_b128 v[28:31], v81 offset:24576
	ds_read_b128 v[32:35], v81 offset:28672
	ds_read_b128 v[36:39], v81 offset:32768
	s_waitcnt vmcnt(32)
	ds_read_b128 v[208:211], v81 offset:16
	ds_read_b128 v[212:215], v81 offset:4112
	ds_read_b128 v[216:219], v81 offset:8208
	ds_read_b128 v[220:223], v81 offset:12304
	ds_read_b128 v[224:227], v81 offset:16400
	ds_read_b128 v[228:231], v81 offset:20496
	ds_read_b128 v[236:239], v81 offset:24592
	ds_read_b128 v[240:243], v81 offset:28688
	ds_read_b128 v[244:247], v81 offset:32784
	s_waitcnt lgkmcnt(9)
	v_fma_f32 v104, v4, v142, v104
	v_fma_f32 v105, v8, v142, v105
	v_fma_f32 v106, v12, v142, v106
	v_fma_f32 v107, v16, v142, v107
	v_fma_f32 v108, v20, v142, v108
	v_fma_f32 v109, v24, v142, v109
	v_fma_f32 v110, v28, v142, v110
	v_fma_f32 v111, v32, v142, v111
	v_fma_f32 v83, v36, v142, v83
	v_fma_f32 v104, v5, v143, v104
	v_fma_f32 v105, v9, v143, v105
	v_fma_f32 v106, v13, v143, v106
	v_fma_f32 v107, v17, v143, v107
	v_fma_f32 v108, v21, v143, v108
	v_fma_f32 v109, v25, v143, v109
	v_fma_f32 v110, v29, v143, v110
	v_fma_f32 v111, v33, v143, v111
	v_fma_f32 v83, v37, v143, v83
	v_fma_f32 v104, v6, v144, v104
	v_fma_f32 v105, v10, v144, v105
	v_fma_f32 v106, v14, v144, v106
	v_fma_f32 v107, v18, v144, v107
	v_fma_f32 v108, v22, v144, v108
	v_fma_f32 v109, v26, v144, v109
	v_fma_f32 v110, v30, v144, v110
	v_fma_f32 v111, v34, v144, v111
	v_fma_f32 v83, v38, v144, v83
	v_fma_f32 v104, v7, v145, v104
	v_fma_f32 v105, v11, v145, v105
	v_fma_f32 v106, v15, v145, v106
	v_fma_f32 v107, v19, v145, v107
	v_fma_f32 v108, v23, v145, v108
	v_fma_f32 v109, v27, v145, v109
	v_fma_f32 v110, v31, v145, v110
	v_fma_f32 v111, v35, v145, v111
	v_fma_f32 v83, v39, v145, v83
	ds_read_b128 v[4:7], v81 offset:32
	ds_read_b128 v[8:11], v81 offset:4128
	ds_read_b128 v[12:15], v81 offset:8224
	ds_read_b128 v[16:19], v81 offset:12320
	ds_read_b128 v[20:23], v81 offset:16416
	ds_read_b128 v[24:27], v81 offset:20512
	ds_read_b128 v[28:31], v81 offset:24608
	ds_read_b128 v[32:35], v81 offset:28704
	ds_read_b128 v[36:39], v81 offset:32800
	s_waitcnt lgkmcnt(9)
	v_fma_f32 v104, v208, v146, v104
	v_fma_f32 v105, v212, v146, v105
	v_fma_f32 v106, v216, v146, v106
	v_fma_f32 v107, v220, v146, v107
	v_fma_f32 v108, v224, v146, v108
	v_fma_f32 v109, v228, v146, v109
	v_fma_f32 v110, v236, v146, v110
	v_fma_f32 v111, v240, v146, v111
	v_fma_f32 v83, v244, v146, v83
	v_fma_f32 v104, v209, v147, v104
	v_fma_f32 v105, v213, v147, v105
	v_fma_f32 v106, v217, v147, v106
	v_fma_f32 v107, v221, v147, v107
	v_fma_f32 v108, v225, v147, v108
	v_fma_f32 v109, v229, v147, v109
	v_fma_f32 v110, v237, v147, v110
	v_fma_f32 v111, v241, v147, v111
	v_fma_f32 v83, v245, v147, v83
	v_fma_f32 v104, v210, v148, v104
	v_fma_f32 v105, v214, v148, v105
	v_fma_f32 v106, v218, v148, v106
	v_fma_f32 v107, v222, v148, v107
	v_fma_f32 v108, v226, v148, v108
	v_fma_f32 v109, v230, v148, v109
	v_fma_f32 v110, v238, v148, v110
	v_fma_f32 v111, v242, v148, v111
	v_fma_f32 v83, v246, v148, v83
	v_fma_f32 v104, v211, v149, v104
	v_fma_f32 v105, v215, v149, v105
	v_fma_f32 v106, v219, v149, v106
	v_fma_f32 v107, v223, v149, v107
	v_fma_f32 v108, v227, v149, v108
	v_fma_f32 v109, v231, v149, v109
	v_fma_f32 v110, v239, v149, v110
	v_fma_f32 v111, v243, v149, v111
	v_fma_f32 v83, v247, v149, v83
	ds_read_b128 v[208:211], v81 offset:48
	ds_read_b128 v[212:215], v81 offset:4144
	ds_read_b128 v[216:219], v81 offset:8240
	ds_read_b128 v[220:223], v81 offset:12336
	ds_read_b128 v[224:227], v81 offset:16432
	ds_read_b128 v[228:231], v81 offset:20528
	ds_read_b128 v[236:239], v81 offset:24624
	ds_read_b128 v[240:243], v81 offset:28720
	ds_read_b128 v[244:247], v81 offset:32816
	s_waitcnt lgkmcnt(9)
; __device__ __forceinline__ void phase0(const Params& p, unsigned char* smem) {
;     ...
;             for (int kk = 0; kk < 128; kk += 4) {
;                 const float w0 = wp[(size_t)(kk + 0) * 3072], w1 = wp[(size_t)(kk + 1) * 3072], w2 = wp[(size_t)(kk + 2) * 3072], w3 = wp[(size_t)(kk + 3) * 3072];
; #pragma unroll
;                 for (int v = 0; v < 9; ++v) {
;                     const float4 sv = *(const float4*)(ssc + v * 1024 + kg * 128 + kk);
;                     acc[v] += sv.x * w0 + sv.y * w1 + sv.z * w2 + sv.w * w3;
;                 }
;             }
	v_fma_f32 v104, v4, v150, v104
	v_fma_f32 v105, v8, v150, v105
	v_fma_f32 v106, v12, v150, v106
	v_fma_f32 v107, v16, v150, v107
	v_fma_f32 v108, v20, v150, v108
	v_fma_f32 v109, v24, v150, v109
	v_fma_f32 v110, v28, v150, v110
	v_fma_f32 v111, v32, v150, v111
	v_fma_f32 v83, v36, v150, v83
	v_fma_f32 v104, v5, v151, v104
	v_fma_f32 v105, v9, v151, v105
	v_fma_f32 v106, v13, v151, v106
	v_fma_f32 v107, v17, v151, v107
	v_fma_f32 v108, v21, v151, v108
	v_fma_f32 v109, v25, v151, v109
	v_fma_f32 v110, v29, v151, v110
	v_fma_f32 v111, v33, v151, v111
	v_fma_f32 v83, v37, v151, v83
	v_fma_f32 v104, v6, v152, v104
	v_fma_f32 v105, v10, v152, v105
	v_fma_f32 v106, v14, v152, v106
	v_fma_f32 v107, v18, v152, v107
	v_fma_f32 v108, v22, v152, v108
	v_fma_f32 v109, v26, v152, v109
	v_fma_f32 v110, v30, v152, v110
	v_fma_f32 v111, v34, v152, v111
	v_fma_f32 v83, v38, v152, v83
	v_fma_f32 v104, v7, v153, v104
	v_fma_f32 v105, v11, v153, v105
	v_fma_f32 v106, v15, v153, v106
	v_fma_f32 v107, v19, v153, v107
	v_fma_f32 v108, v23, v153, v108
	v_fma_f32 v109, v27, v153, v109
	v_fma_f32 v110, v31, v153, v110
	v_fma_f32 v111, v35, v153, v111
	v_fma_f32 v83, v39, v153, v83
	ds_read_b128 v[4:7], v81 offset:64
	ds_read_b128 v[8:11], v81 offset:4160
	ds_read_b128 v[12:15], v81 offset:8256
	ds_read_b128 v[16:19], v81 offset:12352
	ds_read_b128 v[20:23], v81 offset:16448
	ds_read_b128 v[24:27], v81 offset:20544
	ds_read_b128 v[28:31], v81 offset:24640
	ds_read_b128 v[32:35], v81 offset:28736
	ds_read_b128 v[36:39], v81 offset:32832
	s_waitcnt lgkmcnt(9)
	v_fma_f32 v104, v208, v154, v104
	v_fma_f32 v105, v212, v154, v105
	v_fma_f32 v106, v216, v154, v106
	v_fma_f32 v107, v220, v154, v107
	v_fma_f32 v108, v224, v154, v108
	v_fma_f32 v109, v228, v154, v109
	v_fma_f32 v110, v236, v154, v110
	v_fma_f32 v111, v240, v154, v111
	v_fma_f32 v83, v244, v154, v83
	v_fma_f32 v104, v209, v155, v104
	v_fma_f32 v105, v213, v155, v105
	v_fma_f32 v106, v217, v155, v106
	v_fma_f32 v107, v221, v155, v107
	v_fma_f32 v108, v225, v155, v108
	v_fma_f32 v109, v229, v155, v109
	v_fma_f32 v110, v237, v155, v110
	v_fma_f32 v111, v241, v155, v111
	v_fma_f32 v83, v245, v155, v83
	v_fma_f32 v104, v210, v156, v104
	v_fma_f32 v105, v214, v156, v105
	v_fma_f32 v106, v218, v156, v106
	v_fma_f32 v107, v222, v156, v107
	v_fma_f32 v108, v226, v156, v108
	v_fma_f32 v109, v230, v156, v109
	v_fma_f32 v110, v238, v156, v110
	v_fma_f32 v111, v242, v156, v111
	v_fma_f32 v83, v246, v156, v83
	v_fma_f32 v104, v211, v157, v104
	v_fma_f32 v105, v215, v157, v105
	v_fma_f32 v106, v219, v157, v106
	v_fma_f32 v107, v223, v157, v107
	v_fma_f32 v108, v227, v157, v108
	v_fma_f32 v109, v231, v157, v109
	v_fma_f32 v110, v239, v157, v110
	v_fma_f32 v111, v243, v157, v111
	v_fma_f32 v83, v247, v157, v83
	ds_read_b128 v[208:211], v81 offset:80
	ds_read_b128 v[212:215], v81 offset:4176
	ds_read_b128 v[216:219], v81 offset:8272
	ds_read_b128 v[220:223], v81 offset:12368
	ds_read_b128 v[224:227], v81 offset:16464
	ds_read_b128 v[228:231], v81 offset:20560
	ds_read_b128 v[236:239], v81 offset:24656
	ds_read_b128 v[240:243], v81 offset:28752
	ds_read_b128 v[244:247], v81 offset:32848
	s_waitcnt lgkmcnt(9)
	v_fma_f32 v104, v4, v158, v104
	v_fma_f32 v105, v8, v158, v105
	v_fma_f32 v106, v12, v158, v106
	v_fma_f32 v107, v16, v158, v107
	v_fma_f32 v108, v20, v158, v108
	v_fma_f32 v109, v24, v158, v109
	v_fma_f32 v110, v28, v158, v110
	v_fma_f32 v111, v32, v158, v111
	v_fma_f32 v83, v36, v158, v83
	v_fma_f32 v104, v5, v159, v104
	v_fma_f32 v105, v9, v159, v105
	v_fma_f32 v106, v13, v159, v106
	v_fma_f32 v107, v17, v159, v107
	v_fma_f32 v108, v21, v159, v108
	v_fma_f32 v109, v25, v159, v109
	v_fma_f32 v110, v29, v159, v110
	v_fma_f32 v111, v33, v159, v111
	v_fma_f32 v83, v37, v159, v83
	v_fma_f32 v104, v6, v160, v104
	v_fma_f32 v105, v10, v160, v105
	v_fma_f32 v106, v14, v160, v106
	v_fma_f32 v107, v18, v160, v107
	v_fma_f32 v108, v22, v160, v108
	v_fma_f32 v109, v26, v160, v109
	v_fma_f32 v110, v30, v160, v110
	v_fma_f32 v111, v34, v160, v111
	v_fma_f32 v83, v38, v160, v83
	v_fma_f32 v104, v7, v161, v104
	v_fma_f32 v105, v11, v161, v105
	v_fma_f32 v106, v15, v161, v106
	v_fma_f32 v107, v19, v161, v107
	v_fma_f32 v108, v23, v161, v108
	v_fma_f32 v109, v27, v161, v109
	v_fma_f32 v110, v31, v161, v110
	v_fma_f32 v111, v35, v161, v111
	v_fma_f32 v83, v39, v161, v83
	ds_read_b128 v[4:7], v81 offset:96
	ds_read_b128 v[8:11], v81 offset:4192
	ds_read_b128 v[12:15], v81 offset:8288
	ds_read_b128 v[16:19], v81 offset:12384
	ds_read_b128 v[20:23], v81 offset:16480
	ds_read_b128 v[24:27], v81 offset:20576
	ds_read_b128 v[28:31], v81 offset:24672
	ds_read_b128 v[32:35], v81 offset:28768
	ds_read_b128 v[36:39], v81 offset:32864
	s_waitcnt lgkmcnt(9)
	v_fma_f32 v104, v208, v162, v104
	v_fma_f32 v105, v212, v162, v105
	v_fma_f32 v106, v216, v162, v106
	v_fma_f32 v107, v220, v162, v107
	v_fma_f32 v108, v224, v162, v108
	v_fma_f32 v109, v228, v162, v109
	v_fma_f32 v110, v236, v162, v110
	v_fma_f32 v111, v240, v162, v111
	v_fma_f32 v83, v244, v162, v83
	v_fma_f32 v104, v209, v163, v104
	v_fma_f32 v105, v213, v163, v105
	v_fma_f32 v106, v217, v163, v106
	v_fma_f32 v107, v221, v163, v107
	v_fma_f32 v108, v225, v163, v108
	v_fma_f32 v109, v229, v163, v109
	v_fma_f32 v110, v237, v163, v110
	v_fma_f32 v111, v241, v163, v111
	v_fma_f32 v83, v245, v163, v83
	v_fma_f32 v104, v210, v164, v104
	v_fma_f32 v105, v214, v164, v105
	v_fma_f32 v106, v218, v164, v106
	v_fma_f32 v107, v222, v164, v107
	v_fma_f32 v108, v226, v164, v108
	v_fma_f32 v109, v230, v164, v109
	v_fma_f32 v110, v238, v164, v110
	v_fma_f32 v111, v242, v164, v111
	v_fma_f32 v83, v246, v164, v83
	v_fma_f32 v104, v211, v165, v104
	v_fma_f32 v105, v215, v165, v105
	v_fma_f32 v106, v219, v165, v106
	v_fma_f32 v107, v223, v165, v107
	v_fma_f32 v108, v227, v165, v108
	v_fma_f32 v109, v231, v165, v109
	v_fma_f32 v110, v239, v165, v110
	v_fma_f32 v111, v243, v165, v111
	v_fma_f32 v83, v247, v165, v83
	ds_read_b128 v[208:211], v81 offset:112
	ds_read_b128 v[212:215], v81 offset:4208
	ds_read_b128 v[216:219], v81 offset:8304
	ds_read_b128 v[220:223], v81 offset:12400
	ds_read_b128 v[224:227], v81 offset:16496
	ds_read_b128 v[228:231], v81 offset:20592
	ds_read_b128 v[236:239], v81 offset:24688
	ds_read_b128 v[240:243], v81 offset:28784
	ds_read_b128 v[244:247], v81 offset:32880
	s_waitcnt lgkmcnt(9)
; __device__ __forceinline__ void phase0(const Params& p, unsigned char* smem) {
;     ...
;             for (int kk = 0; kk < 128; kk += 4) {
;                 const float w0 = wp[(size_t)(kk + 0) * 3072], w1 = wp[(size_t)(kk + 1) * 3072], w2 = wp[(size_t)(kk + 2) * 3072], w3 = wp[(size_t)(kk + 3) * 3072];
; #pragma unroll
;                 for (int v = 0; v < 9; ++v) {
;                     const float4 sv = *(const float4*)(ssc + v * 1024 + kg * 128 + kk);
;                     acc[v] += sv.x * w0 + sv.y * w1 + sv.z * w2 + sv.w * w3;
;                 }
;             }
	v_fma_f32 v104, v4, v166, v104
	v_fma_f32 v105, v8, v166, v105
	v_fma_f32 v106, v12, v166, v106
	v_fma_f32 v107, v16, v166, v107
	v_fma_f32 v108, v20, v166, v108
	v_fma_f32 v109, v24, v166, v109
	v_fma_f32 v110, v28, v166, v110
	v_fma_f32 v111, v32, v166, v111
	v_fma_f32 v83, v36, v166, v83
	v_fma_f32 v104, v5, v167, v104
	v_fma_f32 v105, v9, v167, v105
	v_fma_f32 v106, v13, v167, v106
	v_fma_f32 v107, v17, v167, v107
	v_fma_f32 v108, v21, v167, v108
	v_fma_f32 v109, v25, v167, v109
	v_fma_f32 v110, v29, v167, v110
	v_fma_f32 v111, v33, v167, v111
	v_fma_f32 v83, v37, v167, v83
	v_fma_f32 v104, v6, v168, v104
	v_fma_f32 v105, v10, v168, v105
	v_fma_f32 v106, v14, v168, v106
	v_fma_f32 v107, v18, v168, v107
	v_fma_f32 v108, v22, v168, v108
	v_fma_f32 v109, v26, v168, v109
	v_fma_f32 v110, v30, v168, v110
	v_fma_f32 v111, v34, v168, v111
	v_fma_f32 v83, v38, v168, v83
	v_fma_f32 v104, v7, v169, v104
	v_fma_f32 v105, v11, v169, v105
	v_fma_f32 v106, v15, v169, v106
	v_fma_f32 v107, v19, v169, v107
	v_fma_f32 v108, v23, v169, v108
	v_fma_f32 v109, v27, v169, v109
	v_fma_f32 v110, v31, v169, v110
	v_fma_f32 v111, v35, v169, v111
	v_fma_f32 v83, v39, v169, v83
	s_waitcnt lgkmcnt(0)
	v_fma_f32 v104, v208, v170, v104
	v_fma_f32 v105, v212, v170, v105
	v_fma_f32 v106, v216, v170, v106
	v_fma_f32 v107, v220, v170, v107
	v_fma_f32 v108, v224, v170, v108
	v_fma_f32 v109, v228, v170, v109
	v_fma_f32 v110, v236, v170, v110
	v_fma_f32 v111, v240, v170, v111
	v_fma_f32 v83, v244, v170, v83
	v_fma_f32 v104, v209, v171, v104
	v_fma_f32 v105, v213, v171, v105
	v_fma_f32 v106, v217, v171, v106
	v_fma_f32 v107, v221, v171, v107
	v_fma_f32 v108, v225, v171, v108
	v_fma_f32 v109, v229, v171, v109
	v_fma_f32 v110, v237, v171, v110
	v_fma_f32 v111, v241, v171, v111
	v_fma_f32 v83, v245, v171, v83
	v_fma_f32 v104, v210, v172, v104
	v_fma_f32 v105, v214, v172, v105
	v_fma_f32 v106, v218, v172, v106
	v_fma_f32 v107, v222, v172, v107
	v_fma_f32 v108, v226, v172, v108
	v_fma_f32 v109, v230, v172, v109
	v_fma_f32 v110, v238, v172, v110
	v_fma_f32 v111, v242, v172, v111
	v_fma_f32 v83, v246, v172, v83
	v_fma_f32 v104, v211, v173, v104
	v_fma_f32 v105, v215, v173, v105
	v_fma_f32 v106, v219, v173, v106
	v_fma_f32 v107, v223, v173, v107
	v_fma_f32 v108, v227, v173, v108
	v_fma_f32 v109, v231, v173, v109
	v_fma_f32 v110, v239, v173, v110
	v_fma_f32 v111, v243, v173, v111
	v_fma_f32 v83, v247, v173, v83
	global_load_dword v142, v40, s[78:79]
	s_add_u32 s78, s78, 0x3000
	s_addc_u32 s79, s79, 0
	global_load_dword v143, v40, s[78:79]
	s_add_u32 s78, s78, 0x3000
	s_addc_u32 s79, s79, 0
	global_load_dword v144, v40, s[78:79]
	s_add_u32 s78, s78, 0x3000
	s_addc_u32 s79, s79, 0
	global_load_dword v145, v40, s[78:79]
	s_add_u32 s78, s78, 0x3000
	s_addc_u32 s79, s79, 0
	global_load_dword v146, v40, s[78:79]
	s_add_u32 s78, s78, 0x3000
	s_addc_u32 s79, s79, 0
	global_load_dword v147, v40, s[78:79]
	s_add_u32 s78, s78, 0x3000
	s_addc_u32 s79, s79, 0
	global_load_dword v148, v40, s[78:79]
	s_add_u32 s78, s78, 0x3000
	s_addc_u32 s79, s79, 0
	global_load_dword v149, v40, s[78:79]
	s_add_u32 s78, s78, 0x3000
	s_addc_u32 s79, s79, 0
	global_load_dword v150, v40, s[78:79]
	s_add_u32 s78, s78, 0x3000
	s_addc_u32 s79, s79, 0
	global_load_dword v151, v40, s[78:79]
	s_add_u32 s78, s78, 0x3000
	s_addc_u32 s79, s79, 0
	global_load_dword v152, v40, s[78:79]
	s_add_u32 s78, s78, 0x3000
	s_addc_u32 s79, s79, 0
	global_load_dword v153, v40, s[78:79]
	s_add_u32 s78, s78, 0x3000
	s_addc_u32 s79, s79, 0
	global_load_dword v154, v40, s[78:79]
	s_add_u32 s78, s78, 0x3000
	s_addc_u32 s79, s79, 0
	global_load_dword v155, v40, s[78:79]
	s_add_u32 s78, s78, 0x3000
	s_addc_u32 s79, s79, 0
	global_load_dword v156, v40, s[78:79]
	s_add_u32 s78, s78, 0x3000
	s_addc_u32 s79, s79, 0
	global_load_dword v157, v40, s[78:79]
	s_add_u32 s78, s78, 0x3000
	s_addc_u32 s79, s79, 0
	global_load_dword v158, v40, s[78:79]
	s_add_u32 s78, s78, 0x3000
	s_addc_u32 s79, s79, 0
	global_load_dword v159, v40, s[78:79]
	s_add_u32 s78, s78, 0x3000
	s_addc_u32 s79, s79, 0
	global_load_dword v160, v40, s[78:79]
	s_add_u32 s78, s78, 0x3000
	s_addc_u32 s79, s79, 0
	global_load_dword v161, v40, s[78:79]
	s_add_u32 s78, s78, 0x3000
	s_addc_u32 s79, s79, 0
	global_load_dword v162, v40, s[78:79]
	s_add_u32 s78, s78, 0x3000
	s_addc_u32 s79, s79, 0
	global_load_dword v163, v40, s[78:79]
	s_add_u32 s78, s78, 0x3000
	s_addc_u32 s79, s79, 0
	global_load_dword v164, v40, s[78:79]
	s_add_u32 s78, s78, 0x3000
	s_addc_u32 s79, s79, 0
	global_load_dword v165, v40, s[78:79]
	s_add_u32 s78, s78, 0x3000
	s_addc_u32 s79, s79, 0
	global_load_dword v166, v40, s[78:79]
	s_add_u32 s78, s78, 0x3000
	s_addc_u32 s79, s79, 0
	global_load_dword v167, v40, s[78:79]
	s_add_u32 s78, s78, 0x3000
	s_addc_u32 s79, s79, 0
	global_load_dword v168, v40, s[78:79]
	s_add_u32 s78, s78, 0x3000
	s_addc_u32 s79, s79, 0
	global_load_dword v169, v40, s[78:79]
	s_add_u32 s78, s78, 0x3000
	s_addc_u32 s79, s79, 0
	global_load_dword v170, v40, s[78:79]
	s_add_u32 s78, s78, 0x3000
	s_addc_u32 s79, s79, 0
	global_load_dword v171, v40, s[78:79]
	s_add_u32 s78, s78, 0x3000
	s_addc_u32 s79, s79, 0
	global_load_dword v172, v40, s[78:79]
	s_add_u32 s78, s78, 0x3000
	s_addc_u32 s79, s79, 0
	global_load_dword v173, v40, s[78:79]
	s_add_u32 s78, s78, 0x3000
	s_addc_u32 s79, s79, 0
	ds_read_b128 v[4:7], v81 offset:128
	ds_read_b128 v[8:11], v81 offset:4224
	ds_read_b128 v[12:15], v81 offset:8320
	ds_read_b128 v[16:19], v81 offset:12416
	ds_read_b128 v[20:23], v81 offset:16512
	ds_read_b128 v[24:27], v81 offset:20608
	ds_read_b128 v[28:31], v81 offset:24704
	ds_read_b128 v[32:35], v81 offset:28800
	ds_read_b128 v[36:39], v81 offset:32896
	s_waitcnt vmcnt(32)
; __device__ __forceinline__ void phase0(const Params& p, unsigned char* smem) {
;     ...
;             for (int kk = 0; kk < 128; kk += 4) {
;                 const float w0 = wp[(size_t)(kk + 0) * 3072], w1 = wp[(size_t)(kk + 1) * 3072], w2 = wp[(size_t)(kk + 2) * 3072], w3 = wp[(size_t)(kk + 3) * 3072];
; #pragma unroll
;                 for (int v = 0; v < 9; ++v) {
;                     const float4 sv = *(const float4*)(ssc + v * 1024 + kg * 128 + kk);
;                     acc[v] += sv.x * w0 + sv.y * w1 + sv.z * w2 + sv.w * w3;
;                 }
;             }
	ds_read_b128 v[208:211], v81 offset:144
	ds_read_b128 v[212:215], v81 offset:4240
	ds_read_b128 v[216:219], v81 offset:8336
	ds_read_b128 v[220:223], v81 offset:12432
	ds_read_b128 v[224:227], v81 offset:16528
	ds_read_b128 v[228:231], v81 offset:20624
	ds_read_b128 v[236:239], v81 offset:24720
	ds_read_b128 v[240:243], v81 offset:28816
	ds_read_b128 v[244:247], v81 offset:32912
	s_waitcnt lgkmcnt(9)
	v_fma_f32 v104, v4, v174, v104
	v_fma_f32 v105, v8, v174, v105
	v_fma_f32 v106, v12, v174, v106
	v_fma_f32 v107, v16, v174, v107
	v_fma_f32 v108, v20, v174, v108
	v_fma_f32 v109, v24, v174, v109
	v_fma_f32 v110, v28, v174, v110
	v_fma_f32 v111, v32, v174, v111
	v_fma_f32 v83, v36, v174, v83
	v_fma_f32 v104, v5, v175, v104
	v_fma_f32 v105, v9, v175, v105
	v_fma_f32 v106, v13, v175, v106
	v_fma_f32 v107, v17, v175, v107
	v_fma_f32 v108, v21, v175, v108
	v_fma_f32 v109, v25, v175, v109
	v_fma_f32 v110, v29, v175, v110
	v_fma_f32 v111, v33, v175, v111
	v_fma_f32 v83, v37, v175, v83
	v_fma_f32 v104, v6, v176, v104
	v_fma_f32 v105, v10, v176, v105
	v_fma_f32 v106, v14, v176, v106
	v_fma_f32 v107, v18, v176, v107
	v_fma_f32 v108, v22, v176, v108
	v_fma_f32 v109, v26, v176, v109
	v_fma_f32 v110, v30, v176, v110
	v_fma_f32 v111, v34, v176, v111
	v_fma_f32 v83, v38, v176, v83
	v_fma_f32 v104, v7, v177, v104
	v_fma_f32 v105, v11, v177, v105
	v_fma_f32 v106, v15, v177, v106
	v_fma_f32 v107, v19, v177, v107
	v_fma_f32 v108, v23, v177, v108
	v_fma_f32 v109, v27, v177, v109
	v_fma_f32 v110, v31, v177, v110
	v_fma_f32 v111, v35, v177, v111
	v_fma_f32 v83, v39, v177, v83
	ds_read_b128 v[4:7], v81 offset:160
	ds_read_b128 v[8:11], v81 offset:4256
	ds_read_b128 v[12:15], v81 offset:8352
	ds_read_b128 v[16:19], v81 offset:12448
	ds_read_b128 v[20:23], v81 offset:16544
	ds_read_b128 v[24:27], v81 offset:20640
	ds_read_b128 v[28:31], v81 offset:24736
	ds_read_b128 v[32:35], v81 offset:28832
	ds_read_b128 v[36:39], v81 offset:32928
	s_waitcnt lgkmcnt(9)
	v_fma_f32 v104, v208, v178, v104
	v_fma_f32 v105, v212, v178, v105
	v_fma_f32 v106, v216, v178, v106
	v_fma_f32 v107, v220, v178, v107
	v_fma_f32 v108, v224, v178, v108
	v_fma_f32 v109, v228, v178, v109
	v_fma_f32 v110, v236, v178, v110
	v_fma_f32 v111, v240, v178, v111
	v_fma_f32 v83, v244, v178, v83
	v_fma_f32 v104, v209, v179, v104
	v_fma_f32 v105, v213, v179, v105
	v_fma_f32 v106, v217, v179, v106
	v_fma_f32 v107, v221, v179, v107
	v_fma_f32 v108, v225, v179, v108
	v_fma_f32 v109, v229, v179, v109
	v_fma_f32 v110, v237, v179, v110
	v_fma_f32 v111, v241, v179, v111
	v_fma_f32 v83, v245, v179, v83
	v_fma_f32 v104, v210, v180, v104
	v_fma_f32 v105, v214, v180, v105
	v_fma_f32 v106, v218, v180, v106
	v_fma_f32 v107, v222, v180, v107
	v_fma_f32 v108, v226, v180, v108
	v_fma_f32 v109, v230, v180, v109
	v_fma_f32 v110, v238, v180, v110
	v_fma_f32 v111, v242, v180, v111
	v_fma_f32 v83, v246, v180, v83
	v_fma_f32 v104, v211, v181, v104
	v_fma_f32 v105, v215, v181, v105
	v_fma_f32 v106, v219, v181, v106
	v_fma_f32 v107, v223, v181, v107
	v_fma_f32 v108, v227, v181, v108
	v_fma_f32 v109, v231, v181, v109
	v_fma_f32 v110, v239, v181, v110
	v_fma_f32 v111, v243, v181, v111
	v_fma_f32 v83, v247, v181, v83
	ds_read_b128 v[208:211], v81 offset:176
	ds_read_b128 v[212:215], v81 offset:4272
	ds_read_b128 v[216:219], v81 offset:8368
	ds_read_b128 v[220:223], v81 offset:12464
	ds_read_b128 v[224:227], v81 offset:16560
	ds_read_b128 v[228:231], v81 offset:20656
	ds_read_b128 v[236:239], v81 offset:24752
	ds_read_b128 v[240:243], v81 offset:28848
	ds_read_b128 v[244:247], v81 offset:32944
	s_waitcnt lgkmcnt(9)
	v_fma_f32 v104, v4, v182, v104
	v_fma_f32 v105, v8, v182, v105
	v_fma_f32 v106, v12, v182, v106
	v_fma_f32 v107, v16, v182, v107
	v_fma_f32 v108, v20, v182, v108
	v_fma_f32 v109, v24, v182, v109
	v_fma_f32 v110, v28, v182, v110
	v_fma_f32 v111, v32, v182, v111
	v_fma_f32 v83, v36, v182, v83
	v_fma_f32 v104, v5, v183, v104
	v_fma_f32 v105, v9, v183, v105
	v_fma_f32 v106, v13, v183, v106
	v_fma_f32 v107, v17, v183, v107
	v_fma_f32 v108, v21, v183, v108
	v_fma_f32 v109, v25, v183, v109
	v_fma_f32 v110, v29, v183, v110
	v_fma_f32 v111, v33, v183, v111
	v_fma_f32 v83, v37, v183, v83
	v_fma_f32 v104, v6, v184, v104
	v_fma_f32 v105, v10, v184, v105
	v_fma_f32 v106, v14, v184, v106
	v_fma_f32 v107, v18, v184, v107
	v_fma_f32 v108, v22, v184, v108
	v_fma_f32 v109, v26, v184, v109
	v_fma_f32 v110, v30, v184, v110
	v_fma_f32 v111, v34, v184, v111
	v_fma_f32 v83, v38, v184, v83
	v_fma_f32 v104, v7, v185, v104
	v_fma_f32 v105, v11, v185, v105
	v_fma_f32 v106, v15, v185, v106
	v_fma_f32 v107, v19, v185, v107
	v_fma_f32 v108, v23, v185, v108
	v_fma_f32 v109, v27, v185, v109
	v_fma_f32 v110, v31, v185, v110
	v_fma_f32 v111, v35, v185, v111
	v_fma_f32 v83, v39, v185, v83
	ds_read_b128 v[4:7], v81 offset:192
	ds_read_b128 v[8:11], v81 offset:4288
	ds_read_b128 v[12:15], v81 offset:8384
	ds_read_b128 v[16:19], v81 offset:12480
	ds_read_b128 v[20:23], v81 offset:16576
	ds_read_b128 v[24:27], v81 offset:20672
	ds_read_b128 v[28:31], v81 offset:24768
	ds_read_b128 v[32:35], v81 offset:28864
	ds_read_b128 v[36:39], v81 offset:32960
	s_waitcnt lgkmcnt(9)
; __device__ __forceinline__ void phase0(const Params& p, unsigned char* smem) {
;     ...
;             for (int kk = 0; kk < 128; kk += 4) {
;                 const float w0 = wp[(size_t)(kk + 0) * 3072], w1 = wp[(size_t)(kk + 1) * 3072], w2 = wp[(size_t)(kk + 2) * 3072], w3 = wp[(size_t)(kk + 3) * 3072];
; #pragma unroll
;                 for (int v = 0; v < 9; ++v) {
;                     const float4 sv = *(const float4*)(ssc + v * 1024 + kg * 128 + kk);
;                     acc[v] += sv.x * w0 + sv.y * w1 + sv.z * w2 + sv.w * w3;
;                 }
;             }
	v_fma_f32 v104, v208, v186, v104
	v_fma_f32 v105, v212, v186, v105
	v_fma_f32 v106, v216, v186, v106
	v_fma_f32 v107, v220, v186, v107
	v_fma_f32 v108, v224, v186, v108
	v_fma_f32 v109, v228, v186, v109
	v_fma_f32 v110, v236, v186, v110
	v_fma_f32 v111, v240, v186, v111
	v_fma_f32 v83, v244, v186, v83
	v_fma_f32 v104, v209, v187, v104
	v_fma_f32 v105, v213, v187, v105
	v_fma_f32 v106, v217, v187, v106
	v_fma_f32 v107, v221, v187, v107
	v_fma_f32 v108, v225, v187, v108
	v_fma_f32 v109, v229, v187, v109
	v_fma_f32 v110, v237, v187, v110
	v_fma_f32 v111, v241, v187, v111
	v_fma_f32 v83, v245, v187, v83
	v_fma_f32 v104, v210, v188, v104
	v_fma_f32 v105, v214, v188, v105
	v_fma_f32 v106, v218, v188, v106
	v_fma_f32 v107, v222, v188, v107
	v_fma_f32 v108, v226, v188, v108
	v_fma_f32 v109, v230, v188, v109
	v_fma_f32 v110, v238, v188, v110
	v_fma_f32 v111, v242, v188, v111
	v_fma_f32 v83, v246, v188, v83
	v_fma_f32 v104, v211, v189, v104
	v_fma_f32 v105, v215, v189, v105
	v_fma_f32 v106, v219, v189, v106
	v_fma_f32 v107, v223, v189, v107
	v_fma_f32 v108, v227, v189, v108
	v_fma_f32 v109, v231, v189, v109
	v_fma_f32 v110, v239, v189, v110
	v_fma_f32 v111, v243, v189, v111
	v_fma_f32 v83, v247, v189, v83
	ds_read_b128 v[208:211], v81 offset:208
	ds_read_b128 v[212:215], v81 offset:4304
	ds_read_b128 v[216:219], v81 offset:8400
	ds_read_b128 v[220:223], v81 offset:12496
	ds_read_b128 v[224:227], v81 offset:16592
	ds_read_b128 v[228:231], v81 offset:20688
	ds_read_b128 v[236:239], v81 offset:24784
	ds_read_b128 v[240:243], v81 offset:28880
	ds_read_b128 v[244:247], v81 offset:32976
	s_waitcnt lgkmcnt(9)
	v_fma_f32 v104, v4, v190, v104
	v_fma_f32 v105, v8, v190, v105
	v_fma_f32 v106, v12, v190, v106
	v_fma_f32 v107, v16, v190, v107
	v_fma_f32 v108, v20, v190, v108
	v_fma_f32 v109, v24, v190, v109
	v_fma_f32 v110, v28, v190, v110
	v_fma_f32 v111, v32, v190, v111
	v_fma_f32 v83, v36, v190, v83
	v_fma_f32 v104, v5, v191, v104
	v_fma_f32 v105, v9, v191, v105
	v_fma_f32 v106, v13, v191, v106
	v_fma_f32 v107, v17, v191, v107
	v_fma_f32 v108, v21, v191, v108
	v_fma_f32 v109, v25, v191, v109
	v_fma_f32 v110, v29, v191, v110
	v_fma_f32 v111, v33, v191, v111
	v_fma_f32 v83, v37, v191, v83
	v_fma_f32 v104, v6, v192, v104
	v_fma_f32 v105, v10, v192, v105
	v_fma_f32 v106, v14, v192, v106
	v_fma_f32 v107, v18, v192, v107
	v_fma_f32 v108, v22, v192, v108
	v_fma_f32 v109, v26, v192, v109
	v_fma_f32 v110, v30, v192, v110
	v_fma_f32 v111, v34, v192, v111
	v_fma_f32 v83, v38, v192, v83
	v_fma_f32 v104, v7, v193, v104
	v_fma_f32 v105, v11, v193, v105
	v_fma_f32 v106, v15, v193, v106
	v_fma_f32 v107, v19, v193, v107
	v_fma_f32 v108, v23, v193, v108
	v_fma_f32 v109, v27, v193, v109
	v_fma_f32 v110, v31, v193, v110
	v_fma_f32 v111, v35, v193, v111
	v_fma_f32 v83, v39, v193, v83
	ds_read_b128 v[4:7], v81 offset:224
	ds_read_b128 v[8:11], v81 offset:4320
	ds_read_b128 v[12:15], v81 offset:8416
	ds_read_b128 v[16:19], v81 offset:12512
	ds_read_b128 v[20:23], v81 offset:16608
	ds_read_b128 v[24:27], v81 offset:20704
	ds_read_b128 v[28:31], v81 offset:24800
	ds_read_b128 v[32:35], v81 offset:28896
	ds_read_b128 v[36:39], v81 offset:32992
	s_waitcnt lgkmcnt(9)
	v_fma_f32 v104, v208, v194, v104
	v_fma_f32 v105, v212, v194, v105
	v_fma_f32 v106, v216, v194, v106
	v_fma_f32 v107, v220, v194, v107
	v_fma_f32 v108, v224, v194, v108
	v_fma_f32 v109, v228, v194, v109
	v_fma_f32 v110, v236, v194, v110
	v_fma_f32 v111, v240, v194, v111
	v_fma_f32 v83, v244, v194, v83
	v_fma_f32 v104, v209, v195, v104
	v_fma_f32 v105, v213, v195, v105
	v_fma_f32 v106, v217, v195, v106
	v_fma_f32 v107, v221, v195, v107
	v_fma_f32 v108, v225, v195, v108
	v_fma_f32 v109, v229, v195, v109
	v_fma_f32 v110, v237, v195, v110
	v_fma_f32 v111, v241, v195, v111
	v_fma_f32 v83, v245, v195, v83
	v_fma_f32 v104, v210, v196, v104
	v_fma_f32 v105, v214, v196, v105
	v_fma_f32 v106, v218, v196, v106
	v_fma_f32 v107, v222, v196, v107
	v_fma_f32 v108, v226, v196, v108
	v_fma_f32 v109, v230, v196, v109
	v_fma_f32 v110, v238, v196, v110
	v_fma_f32 v111, v242, v196, v111
	v_fma_f32 v83, v246, v196, v83
	v_fma_f32 v104, v211, v197, v104
	v_fma_f32 v105, v215, v197, v105
	v_fma_f32 v106, v219, v197, v106
	v_fma_f32 v107, v223, v197, v107
	v_fma_f32 v108, v227, v197, v108
	v_fma_f32 v109, v231, v197, v109
	v_fma_f32 v110, v239, v197, v110
	v_fma_f32 v111, v243, v197, v111
	v_fma_f32 v83, v247, v197, v83
	ds_read_b128 v[208:211], v81 offset:240
	ds_read_b128 v[212:215], v81 offset:4336
	ds_read_b128 v[216:219], v81 offset:8432
	ds_read_b128 v[220:223], v81 offset:12528
	ds_read_b128 v[224:227], v81 offset:16624
	ds_read_b128 v[228:231], v81 offset:20720
	ds_read_b128 v[236:239], v81 offset:24816
	ds_read_b128 v[240:243], v81 offset:28912
	ds_read_b128 v[244:247], v81 offset:33008
	s_waitcnt lgkmcnt(9)
	v_fma_f32 v104, v4, v198, v104
	v_fma_f32 v105, v8, v198, v105
	v_fma_f32 v106, v12, v198, v106
	v_fma_f32 v107, v16, v198, v107
	v_fma_f32 v108, v20, v198, v108
	v_fma_f32 v109, v24, v198, v109
	v_fma_f32 v110, v28, v198, v110
	v_fma_f32 v111, v32, v198, v111
	v_fma_f32 v83, v36, v198, v83
	v_fma_f32 v104, v5, v199, v104
	v_fma_f32 v105, v9, v199, v105
	v_fma_f32 v106, v13, v199, v106
	v_fma_f32 v107, v17, v199, v107
	v_fma_f32 v108, v21, v199, v108
	v_fma_f32 v109, v25, v199, v109
	v_fma_f32 v110, v29, v199, v110
	v_fma_f32 v111, v33, v199, v111
	v_fma_f32 v83, v37, v199, v83
	v_fma_f32 v104, v6, v200, v104
	v_fma_f32 v105, v10, v200, v105
	v_fma_f32 v106, v14, v200, v106
	v_fma_f32 v107, v18, v200, v107
	v_fma_f32 v108, v22, v200, v108
	v_fma_f32 v109, v26, v200, v109
	v_fma_f32 v110, v30, v200, v110
	v_fma_f32 v111, v34, v200, v111
	v_fma_f32 v83, v38, v200, v83
	v_fma_f32 v104, v7, v201, v104
	v_fma_f32 v105, v11, v201, v105
	v_fma_f32 v106, v15, v201, v106
	v_fma_f32 v107, v19, v201, v107
	v_fma_f32 v108, v23, v201, v108
	v_fma_f32 v109, v27, v201, v109
	v_fma_f32 v110, v31, v201, v110
	v_fma_f32 v111, v35, v201, v111
	v_fma_f32 v83, v39, v201, v83
	s_waitcnt lgkmcnt(0)
; __device__ __forceinline__ void phase0(const Params& p, unsigned char* smem) {
;     ...
;             const float* wp = p.ada_w + ((size_t)l * 1024 + kg * 128) * 3072 + n0 + col;
; #pragma unroll 2
;             for (int kk = 0; kk < 128; kk += 4) {
;                 const float w0 = wp[(size_t)(kk + 0) * 3072], w1 = wp[(size_t)(kk + 1) * 3072], w2 = wp[(size_t)(kk + 2) * 3072], w3 = wp[(size_t)(kk + 3) * 3072];
; #pragma unroll
;                 for (int v = 0; v < 9; ++v) {
;                     const float4 sv = *(const float4*)(ssc + v * 1024 + kg * 128 + kk);
;                     acc[v] += sv.x * w0 + sv.y * w1 + sv.z * w2 + sv.w * w3;
;                 }
;             }
	v_fma_f32 v104, v208, v202, v104
	v_fma_f32 v105, v212, v202, v105
	v_fma_f32 v106, v216, v202, v106
	v_fma_f32 v107, v220, v202, v107
	v_fma_f32 v108, v224, v202, v108
	v_fma_f32 v109, v228, v202, v109
	v_fma_f32 v110, v236, v202, v110
	v_fma_f32 v111, v240, v202, v111
	v_fma_f32 v83, v244, v202, v83
	v_fma_f32 v104, v209, v203, v104
	v_fma_f32 v105, v213, v203, v105
	v_fma_f32 v106, v217, v203, v106
	v_fma_f32 v107, v221, v203, v107
	v_fma_f32 v108, v225, v203, v108
	v_fma_f32 v109, v229, v203, v109
	v_fma_f32 v110, v237, v203, v110
	v_fma_f32 v111, v241, v203, v111
	v_fma_f32 v83, v245, v203, v83
	v_fma_f32 v104, v210, v204, v104
	v_fma_f32 v105, v214, v204, v105
	v_fma_f32 v106, v218, v204, v106
	v_fma_f32 v107, v222, v204, v107
	v_fma_f32 v108, v226, v204, v108
	v_fma_f32 v109, v230, v204, v109
	v_fma_f32 v110, v238, v204, v110
	v_fma_f32 v111, v242, v204, v111
	v_fma_f32 v83, v246, v204, v83
	v_fma_f32 v104, v211, v205, v104
	v_fma_f32 v105, v215, v205, v105
	v_fma_f32 v106, v219, v205, v106
	v_fma_f32 v107, v223, v205, v107
	v_fma_f32 v108, v227, v205, v108
	v_fma_f32 v109, v231, v205, v109
	v_fma_f32 v110, v239, v205, v110
	v_fma_f32 v111, v243, v205, v111
	v_fma_f32 v83, v247, v205, v83
	global_load_dword v174, v40, s[78:79]
	s_add_u32 s78, s78, 0x3000
	s_addc_u32 s79, s79, 0
	global_load_dword v175, v40, s[78:79]
	s_add_u32 s78, s78, 0x3000
	s_addc_u32 s79, s79, 0
	global_load_dword v176, v40, s[78:79]
	s_add_u32 s78, s78, 0x3000
	s_addc_u32 s79, s79, 0
	global_load_dword v177, v40, s[78:79]
	s_add_u32 s78, s78, 0x3000
	s_addc_u32 s79, s79, 0
	global_load_dword v178, v40, s[78:79]
	s_add_u32 s78, s78, 0x3000
	s_addc_u32 s79, s79, 0
	global_load_dword v179, v40, s[78:79]
	s_add_u32 s78, s78, 0x3000
	s_addc_u32 s79, s79, 0
	global_load_dword v180, v40, s[78:79]
	s_add_u32 s78, s78, 0x3000
	s_addc_u32 s79, s79, 0
	global_load_dword v181, v40, s[78:79]
	s_add_u32 s78, s78, 0x3000
	s_addc_u32 s79, s79, 0
	global_load_dword v182, v40, s[78:79]
	s_add_u32 s78, s78, 0x3000
	s_addc_u32 s79, s79, 0
	global_load_dword v183, v40, s[78:79]
	s_add_u32 s78, s78, 0x3000
	s_addc_u32 s79, s79, 0
	global_load_dword v184, v40, s[78:79]
	s_add_u32 s78, s78, 0x3000
	s_addc_u32 s79, s79, 0
	global_load_dword v185, v40, s[78:79]
	s_add_u32 s78, s78, 0x3000
	s_addc_u32 s79, s79, 0
	global_load_dword v186, v40, s[78:79]
	s_add_u32 s78, s78, 0x3000
	s_addc_u32 s79, s79, 0
	global_load_dword v187, v40, s[78:79]
	s_add_u32 s78, s78, 0x3000
	s_addc_u32 s79, s79, 0
	global_load_dword v188, v40, s[78:79]
	s_add_u32 s78, s78, 0x3000
	s_addc_u32 s79, s79, 0
	global_load_dword v189, v40, s[78:79]
	s_add_u32 s78, s78, 0x3000
	s_addc_u32 s79, s79, 0
	global_load_dword v190, v40, s[78:79]
	s_add_u32 s78, s78, 0x3000
	s_addc_u32 s79, s79, 0
	global_load_dword v191, v40, s[78:79]
	s_add_u32 s78, s78, 0x3000
	s_addc_u32 s79, s79, 0
	global_load_dword v192, v40, s[78:79]
	s_add_u32 s78, s78, 0x3000
	s_addc_u32 s79, s79, 0
	global_load_dword v193, v40, s[78:79]
	s_add_u32 s78, s78, 0x3000
	s_addc_u32 s79, s79, 0
	global_load_dword v194, v40, s[78:79]
	s_add_u32 s78, s78, 0x3000
	s_addc_u32 s79, s79, 0
	global_load_dword v195, v40, s[78:79]
	s_add_u32 s78, s78, 0x3000
	s_addc_u32 s79, s79, 0
	global_load_dword v196, v40, s[78:79]
	s_add_u32 s78, s78, 0x3000
	s_addc_u32 s79, s79, 0
	global_load_dword v197, v40, s[78:79]
	s_add_u32 s78, s78, 0x3000
	s_addc_u32 s79, s79, 0
	global_load_dword v198, v40, s[78:79]
	s_add_u32 s78, s78, 0x3000
	s_addc_u32 s79, s79, 0
	global_load_dword v199, v40, s[78:79]
	s_add_u32 s78, s78, 0x3000
	s_addc_u32 s79, s79, 0
	global_load_dword v200, v40, s[78:79]
	s_add_u32 s78, s78, 0x3000
	s_addc_u32 s79, s79, 0
	global_load_dword v201, v40, s[78:79]
	s_add_u32 s78, s78, 0x3000
	s_addc_u32 s79, s79, 0
	global_load_dword v202, v40, s[78:79]
	s_add_u32 s78, s78, 0x3000
	s_addc_u32 s79, s79, 0
	global_load_dword v203, v40, s[78:79]
	s_add_u32 s78, s78, 0x3000
	s_addc_u32 s79, s79, 0
	global_load_dword v204, v40, s[78:79]
	s_add_u32 s78, s78, 0x3000
	s_addc_u32 s79, s79, 0
	global_load_dword v205, v40, s[78:79]
	s_add_u32 s78, s78, 0x3000
	s_addc_u32 s79, s79, 0
	ds_read_b128 v[4:7], v81 offset:256
	ds_read_b128 v[8:11], v81 offset:4352
	ds_read_b128 v[12:15], v81 offset:8448
	ds_read_b128 v[16:19], v81 offset:12544
	ds_read_b128 v[20:23], v81 offset:16640
	ds_read_b128 v[24:27], v81 offset:20736
	ds_read_b128 v[28:31], v81 offset:24832
	ds_read_b128 v[32:35], v81 offset:28928
	ds_read_b128 v[36:39], v81 offset:33024
	s_waitcnt vmcnt(32)
	ds_read_b128 v[208:211], v81 offset:272
	ds_read_b128 v[212:215], v81 offset:4368
	ds_read_b128 v[216:219], v81 offset:8464
	ds_read_b128 v[220:223], v81 offset:12560
	ds_read_b128 v[224:227], v81 offset:16656
	ds_read_b128 v[228:231], v81 offset:20752
	ds_read_b128 v[236:239], v81 offset:24848
	ds_read_b128 v[240:243], v81 offset:28944
	ds_read_b128 v[244:247], v81 offset:33040
	s_waitcnt lgkmcnt(9)
; __device__ __forceinline__ void phase0(const Params& p, unsigned char* smem) {
;     ...
;             for (int kk = 0; kk < 128; kk += 4) {
;                 const float w0 = wp[(size_t)(kk + 0) * 3072], w1 = wp[(size_t)(kk + 1) * 3072], w2 = wp[(size_t)(kk + 2) * 3072], w3 = wp[(size_t)(kk + 3) * 3072];
; #pragma unroll
;                 for (int v = 0; v < 9; ++v) {
;                     const float4 sv = *(const float4*)(ssc + v * 1024 + kg * 128 + kk);
;                     acc[v] += sv.x * w0 + sv.y * w1 + sv.z * w2 + sv.w * w3;
;                 }
;             }
	v_fma_f32 v104, v4, v142, v104
	v_fma_f32 v105, v8, v142, v105
	v_fma_f32 v106, v12, v142, v106
	v_fma_f32 v107, v16, v142, v107
	v_fma_f32 v108, v20, v142, v108
	v_fma_f32 v109, v24, v142, v109
	v_fma_f32 v110, v28, v142, v110
	v_fma_f32 v111, v32, v142, v111
	v_fma_f32 v83, v36, v142, v83
	v_fma_f32 v104, v5, v143, v104
	v_fma_f32 v105, v9, v143, v105
	v_fma_f32 v106, v13, v143, v106
	v_fma_f32 v107, v17, v143, v107
	v_fma_f32 v108, v21, v143, v108
	v_fma_f32 v109, v25, v143, v109
	v_fma_f32 v110, v29, v143, v110
	v_fma_f32 v111, v33, v143, v111
	v_fma_f32 v83, v37, v143, v83
	v_fma_f32 v104, v6, v144, v104
	v_fma_f32 v105, v10, v144, v105
	v_fma_f32 v106, v14, v144, v106
	v_fma_f32 v107, v18, v144, v107
	v_fma_f32 v108, v22, v144, v108
	v_fma_f32 v109, v26, v144, v109
	v_fma_f32 v110, v30, v144, v110
	v_fma_f32 v111, v34, v144, v111
	v_fma_f32 v83, v38, v144, v83
	v_fma_f32 v104, v7, v145, v104
	v_fma_f32 v105, v11, v145, v105
	v_fma_f32 v106, v15, v145, v106
	v_fma_f32 v107, v19, v145, v107
	v_fma_f32 v108, v23, v145, v108
	v_fma_f32 v109, v27, v145, v109
	v_fma_f32 v110, v31, v145, v110
	v_fma_f32 v111, v35, v145, v111
	v_fma_f32 v83, v39, v145, v83
	ds_read_b128 v[4:7], v81 offset:288
	ds_read_b128 v[8:11], v81 offset:4384
	ds_read_b128 v[12:15], v81 offset:8480
	ds_read_b128 v[16:19], v81 offset:12576
	ds_read_b128 v[20:23], v81 offset:16672
	ds_read_b128 v[24:27], v81 offset:20768
	ds_read_b128 v[28:31], v81 offset:24864
	ds_read_b128 v[32:35], v81 offset:28960
	ds_read_b128 v[36:39], v81 offset:33056
	s_waitcnt lgkmcnt(9)
	v_fma_f32 v104, v208, v146, v104
	v_fma_f32 v105, v212, v146, v105
	v_fma_f32 v106, v216, v146, v106
	v_fma_f32 v107, v220, v146, v107
	v_fma_f32 v108, v224, v146, v108
	v_fma_f32 v109, v228, v146, v109
	v_fma_f32 v110, v236, v146, v110
	v_fma_f32 v111, v240, v146, v111
	v_fma_f32 v83, v244, v146, v83
	v_fma_f32 v104, v209, v147, v104
	v_fma_f32 v105, v213, v147, v105
	v_fma_f32 v106, v217, v147, v106
	v_fma_f32 v107, v221, v147, v107
	v_fma_f32 v108, v225, v147, v108
	v_fma_f32 v109, v229, v147, v109
	v_fma_f32 v110, v237, v147, v110
	v_fma_f32 v111, v241, v147, v111
	v_fma_f32 v83, v245, v147, v83
	v_fma_f32 v104, v210, v148, v104
	v_fma_f32 v105, v214, v148, v105
	v_fma_f32 v106, v218, v148, v106
	v_fma_f32 v107, v222, v148, v107
	v_fma_f32 v108, v226, v148, v108
	v_fma_f32 v109, v230, v148, v109
	v_fma_f32 v110, v238, v148, v110
	v_fma_f32 v111, v242, v148, v111
	v_fma_f32 v83, v246, v148, v83
	v_fma_f32 v104, v211, v149, v104
	v_fma_f32 v105, v215, v149, v105
	v_fma_f32 v106, v219, v149, v106
	v_fma_f32 v107, v223, v149, v107
	v_fma_f32 v108, v227, v149, v108
	v_fma_f32 v109, v231, v149, v109
	v_fma_f32 v110, v239, v149, v110
	v_fma_f32 v111, v243, v149, v111
	v_fma_f32 v83, v247, v149, v83
	ds_read_b128 v[208:211], v81 offset:304
	ds_read_b128 v[212:215], v81 offset:4400
	ds_read_b128 v[216:219], v81 offset:8496
	ds_read_b128 v[220:223], v81 offset:12592
	ds_read_b128 v[224:227], v81 offset:16688
	ds_read_b128 v[228:231], v81 offset:20784
	ds_read_b128 v[236:239], v81 offset:24880
	ds_read_b128 v[240:243], v81 offset:28976
	ds_read_b128 v[244:247], v81 offset:33072
	s_waitcnt lgkmcnt(9)
	v_fma_f32 v104, v4, v150, v104
	v_fma_f32 v105, v8, v150, v105
	v_fma_f32 v106, v12, v150, v106
	v_fma_f32 v107, v16, v150, v107
	v_fma_f32 v108, v20, v150, v108
	v_fma_f32 v109, v24, v150, v109
	v_fma_f32 v110, v28, v150, v110
	v_fma_f32 v111, v32, v150, v111
	v_fma_f32 v83, v36, v150, v83
	v_fma_f32 v104, v5, v151, v104
	v_fma_f32 v105, v9, v151, v105
	v_fma_f32 v106, v13, v151, v106
	v_fma_f32 v107, v17, v151, v107
	v_fma_f32 v108, v21, v151, v108
	v_fma_f32 v109, v25, v151, v109
	v_fma_f32 v110, v29, v151, v110
	v_fma_f32 v111, v33, v151, v111
	v_fma_f32 v83, v37, v151, v83
	v_fma_f32 v104, v6, v152, v104
	v_fma_f32 v105, v10, v152, v105
	v_fma_f32 v106, v14, v152, v106
	v_fma_f32 v107, v18, v152, v107
	v_fma_f32 v108, v22, v152, v108
	v_fma_f32 v109, v26, v152, v109
	v_fma_f32 v110, v30, v152, v110
	v_fma_f32 v111, v34, v152, v111
	v_fma_f32 v83, v38, v152, v83
	v_fma_f32 v104, v7, v153, v104
	v_fma_f32 v105, v11, v153, v105
	v_fma_f32 v106, v15, v153, v106
	v_fma_f32 v107, v19, v153, v107
	v_fma_f32 v108, v23, v153, v108
	v_fma_f32 v109, v27, v153, v109
	v_fma_f32 v110, v31, v153, v110
	v_fma_f32 v111, v35, v153, v111
	v_fma_f32 v83, v39, v153, v83
	ds_read_b128 v[4:7], v81 offset:320
	ds_read_b128 v[8:11], v81 offset:4416
	ds_read_b128 v[12:15], v81 offset:8512
	ds_read_b128 v[16:19], v81 offset:12608
	ds_read_b128 v[20:23], v81 offset:16704
	ds_read_b128 v[24:27], v81 offset:20800
	ds_read_b128 v[28:31], v81 offset:24896
	ds_read_b128 v[32:35], v81 offset:28992
	ds_read_b128 v[36:39], v81 offset:33088
	s_waitcnt lgkmcnt(9)
	v_fma_f32 v104, v208, v154, v104
	v_fma_f32 v105, v212, v154, v105
	v_fma_f32 v106, v216, v154, v106
	v_fma_f32 v107, v220, v154, v107
	v_fma_f32 v108, v224, v154, v108
	v_fma_f32 v109, v228, v154, v109
	v_fma_f32 v110, v236, v154, v110
	v_fma_f32 v111, v240, v154, v111
	v_fma_f32 v83, v244, v154, v83
	v_fma_f32 v104, v209, v155, v104
	v_fma_f32 v105, v213, v155, v105
	v_fma_f32 v106, v217, v155, v106
	v_fma_f32 v107, v221, v155, v107
	v_fma_f32 v108, v225, v155, v108
	v_fma_f32 v109, v229, v155, v109
	v_fma_f32 v110, v237, v155, v110
	v_fma_f32 v111, v241, v155, v111
	v_fma_f32 v83, v245, v155, v83
	v_fma_f32 v104, v210, v156, v104
	v_fma_f32 v105, v214, v156, v105
	v_fma_f32 v106, v218, v156, v106
	v_fma_f32 v107, v222, v156, v107
	v_fma_f32 v108, v226, v156, v108
	v_fma_f32 v109, v230, v156, v109
	v_fma_f32 v110, v238, v156, v110
	v_fma_f32 v111, v242, v156, v111
	v_fma_f32 v83, v246, v156, v83
	v_fma_f32 v104, v211, v157, v104
	v_fma_f32 v105, v215, v157, v105
	v_fma_f32 v106, v219, v157, v106
	v_fma_f32 v107, v223, v157, v107
	v_fma_f32 v108, v227, v157, v108
	v_fma_f32 v109, v231, v157, v109
	v_fma_f32 v110, v239, v157, v110
	v_fma_f32 v111, v243, v157, v111
	v_fma_f32 v83, v247, v157, v83
	ds_read_b128 v[208:211], v81 offset:336
	ds_read_b128 v[212:215], v81 offset:4432
	ds_read_b128 v[216:219], v81 offset:8528
	ds_read_b128 v[220:223], v81 offset:12624
	ds_read_b128 v[224:227], v81 offset:16720
	ds_read_b128 v[228:231], v81 offset:20816
	ds_read_b128 v[236:239], v81 offset:24912
	ds_read_b128 v[240:243], v81 offset:29008
	ds_read_b128 v[244:247], v81 offset:33104
	s_waitcnt lgkmcnt(9)
; __device__ __forceinline__ void phase0(const Params& p, unsigned char* smem) {
;     ...
;             for (int kk = 0; kk < 128; kk += 4) {
;                 const float w0 = wp[(size_t)(kk + 0) * 3072], w1 = wp[(size_t)(kk + 1) * 3072], w2 = wp[(size_t)(kk + 2) * 3072], w3 = wp[(size_t)(kk + 3) * 3072];
; #pragma unroll
;                 for (int v = 0; v < 9; ++v) {
;                     const float4 sv = *(const float4*)(ssc + v * 1024 + kg * 128 + kk);
;                     acc[v] += sv.x * w0 + sv.y * w1 + sv.z * w2 + sv.w * w3;
;                 }
;             }
	v_fma_f32 v104, v4, v158, v104
	v_fma_f32 v105, v8, v158, v105
	v_fma_f32 v106, v12, v158, v106
	v_fma_f32 v107, v16, v158, v107
	v_fma_f32 v108, v20, v158, v108
	v_fma_f32 v109, v24, v158, v109
	v_fma_f32 v110, v28, v158, v110
	v_fma_f32 v111, v32, v158, v111
	v_fma_f32 v83, v36, v158, v83
	v_fma_f32 v104, v5, v159, v104
	v_fma_f32 v105, v9, v159, v105
	v_fma_f32 v106, v13, v159, v106
	v_fma_f32 v107, v17, v159, v107
	v_fma_f32 v108, v21, v159, v108
	v_fma_f32 v109, v25, v159, v109
	v_fma_f32 v110, v29, v159, v110
	v_fma_f32 v111, v33, v159, v111
	v_fma_f32 v83, v37, v159, v83
	v_fma_f32 v104, v6, v160, v104
	v_fma_f32 v105, v10, v160, v105
	v_fma_f32 v106, v14, v160, v106
	v_fma_f32 v107, v18, v160, v107
	v_fma_f32 v108, v22, v160, v108
	v_fma_f32 v109, v26, v160, v109
	v_fma_f32 v110, v30, v160, v110
	v_fma_f32 v111, v34, v160, v111
	v_fma_f32 v83, v38, v160, v83
	v_fma_f32 v104, v7, v161, v104
	v_fma_f32 v105, v11, v161, v105
	v_fma_f32 v106, v15, v161, v106
	v_fma_f32 v107, v19, v161, v107
	v_fma_f32 v108, v23, v161, v108
	v_fma_f32 v109, v27, v161, v109
	v_fma_f32 v110, v31, v161, v110
	v_fma_f32 v111, v35, v161, v111
	v_fma_f32 v83, v39, v161, v83
	ds_read_b128 v[4:7], v81 offset:352
	ds_read_b128 v[8:11], v81 offset:4448
	ds_read_b128 v[12:15], v81 offset:8544
	ds_read_b128 v[16:19], v81 offset:12640
	ds_read_b128 v[20:23], v81 offset:16736
	ds_read_b128 v[24:27], v81 offset:20832
	ds_read_b128 v[28:31], v81 offset:24928
	ds_read_b128 v[32:35], v81 offset:29024
	ds_read_b128 v[36:39], v81 offset:33120
	s_waitcnt lgkmcnt(9)
	v_fma_f32 v104, v208, v162, v104
	v_fma_f32 v105, v212, v162, v105
	v_fma_f32 v106, v216, v162, v106
	v_fma_f32 v107, v220, v162, v107
	v_fma_f32 v108, v224, v162, v108
	v_fma_f32 v109, v228, v162, v109
	v_fma_f32 v110, v236, v162, v110
	v_fma_f32 v111, v240, v162, v111
	v_fma_f32 v83, v244, v162, v83
	v_fma_f32 v104, v209, v163, v104
	v_fma_f32 v105, v213, v163, v105
	v_fma_f32 v106, v217, v163, v106
	v_fma_f32 v107, v221, v163, v107
	v_fma_f32 v108, v225, v163, v108
	v_fma_f32 v109, v229, v163, v109
	v_fma_f32 v110, v237, v163, v110
	v_fma_f32 v111, v241, v163, v111
	v_fma_f32 v83, v245, v163, v83
	v_fma_f32 v104, v210, v164, v104
	v_fma_f32 v105, v214, v164, v105
	v_fma_f32 v106, v218, v164, v106
	v_fma_f32 v107, v222, v164, v107
	v_fma_f32 v108, v226, v164, v108
	v_fma_f32 v109, v230, v164, v109
	v_fma_f32 v110, v238, v164, v110
	v_fma_f32 v111, v242, v164, v111
	v_fma_f32 v83, v246, v164, v83
	v_fma_f32 v104, v211, v165, v104
	v_fma_f32 v105, v215, v165, v105
	v_fma_f32 v106, v219, v165, v106
	v_fma_f32 v107, v223, v165, v107
	v_fma_f32 v108, v227, v165, v108
	v_fma_f32 v109, v231, v165, v109
	v_fma_f32 v110, v239, v165, v110
	v_fma_f32 v111, v243, v165, v111
	v_fma_f32 v83, v247, v165, v83
	ds_read_b128 v[208:211], v81 offset:368
	ds_read_b128 v[212:215], v81 offset:4464
	ds_read_b128 v[216:219], v81 offset:8560
	ds_read_b128 v[220:223], v81 offset:12656
	ds_read_b128 v[224:227], v81 offset:16752
	ds_read_b128 v[228:231], v81 offset:20848
	ds_read_b128 v[236:239], v81 offset:24944
	ds_read_b128 v[240:243], v81 offset:29040
	ds_read_b128 v[244:247], v81 offset:33136
	s_waitcnt lgkmcnt(9)
	v_fma_f32 v104, v4, v166, v104
	v_fma_f32 v105, v8, v166, v105
	v_fma_f32 v106, v12, v166, v106
	v_fma_f32 v107, v16, v166, v107
	v_fma_f32 v108, v20, v166, v108
	v_fma_f32 v109, v24, v166, v109
	v_fma_f32 v110, v28, v166, v110
	v_fma_f32 v111, v32, v166, v111
	v_fma_f32 v83, v36, v166, v83
	v_fma_f32 v104, v5, v167, v104
	v_fma_f32 v105, v9, v167, v105
	v_fma_f32 v106, v13, v167, v106
	v_fma_f32 v107, v17, v167, v107
	v_fma_f32 v108, v21, v167, v108
	v_fma_f32 v109, v25, v167, v109
	v_fma_f32 v110, v29, v167, v110
	v_fma_f32 v111, v33, v167, v111
	v_fma_f32 v83, v37, v167, v83
	v_fma_f32 v104, v6, v168, v104
	v_fma_f32 v105, v10, v168, v105
	v_fma_f32 v106, v14, v168, v106
	v_fma_f32 v107, v18, v168, v107
	v_fma_f32 v108, v22, v168, v108
	v_fma_f32 v109, v26, v168, v109
	v_fma_f32 v110, v30, v168, v110
	v_fma_f32 v111, v34, v168, v111
	v_fma_f32 v83, v38, v168, v83
	v_fma_f32 v104, v7, v169, v104
	v_fma_f32 v105, v11, v169, v105
	v_fma_f32 v106, v15, v169, v106
	v_fma_f32 v107, v19, v169, v107
	v_fma_f32 v108, v23, v169, v108
	v_fma_f32 v109, v27, v169, v109
	v_fma_f32 v110, v31, v169, v110
	v_fma_f32 v111, v35, v169, v111
	v_fma_f32 v83, v39, v169, v83
	s_waitcnt lgkmcnt(0)
	v_fma_f32 v104, v208, v170, v104
	v_fma_f32 v105, v212, v170, v105
	v_fma_f32 v106, v216, v170, v106
	v_fma_f32 v107, v220, v170, v107
	v_fma_f32 v108, v224, v170, v108
	v_fma_f32 v109, v228, v170, v109
	v_fma_f32 v110, v236, v170, v110
	v_fma_f32 v111, v240, v170, v111
	v_fma_f32 v83, v244, v170, v83
	v_fma_f32 v104, v209, v171, v104
	v_fma_f32 v105, v213, v171, v105
	v_fma_f32 v106, v217, v171, v106
	v_fma_f32 v107, v221, v171, v107
	v_fma_f32 v108, v225, v171, v108
	v_fma_f32 v109, v229, v171, v109
	v_fma_f32 v110, v237, v171, v110
	v_fma_f32 v111, v241, v171, v111
	v_fma_f32 v83, v245, v171, v83
	v_fma_f32 v104, v210, v172, v104
	v_fma_f32 v105, v214, v172, v105
	v_fma_f32 v106, v218, v172, v106
	v_fma_f32 v107, v222, v172, v107
	v_fma_f32 v108, v226, v172, v108
	v_fma_f32 v109, v230, v172, v109
	v_fma_f32 v110, v238, v172, v110
	v_fma_f32 v111, v242, v172, v111
	v_fma_f32 v83, v246, v172, v83
	v_fma_f32 v104, v211, v173, v104
	v_fma_f32 v105, v215, v173, v105
	v_fma_f32 v106, v219, v173, v106
	v_fma_f32 v107, v223, v173, v107
	v_fma_f32 v108, v227, v173, v108
	v_fma_f32 v109, v231, v173, v109
	v_fma_f32 v110, v239, v173, v110
	v_fma_f32 v111, v243, v173, v111
	v_fma_f32 v83, v247, v173, v83
	ds_read_b128 v[4:7], v81 offset:384
	ds_read_b128 v[8:11], v81 offset:4480
	ds_read_b128 v[12:15], v81 offset:8576
	ds_read_b128 v[16:19], v81 offset:12672
	ds_read_b128 v[20:23], v81 offset:16768
	ds_read_b128 v[24:27], v81 offset:20864
	ds_read_b128 v[28:31], v81 offset:24960
	ds_read_b128 v[32:35], v81 offset:29056
	ds_read_b128 v[36:39], v81 offset:33152
	s_waitcnt vmcnt(0)
; __device__ __forceinline__ void phase0(const Params& p, unsigned char* smem) {
;     ...
;             for (int kk = 0; kk < 128; kk += 4) {
;                 const float w0 = wp[(size_t)(kk + 0) * 3072], w1 = wp[(size_t)(kk + 1) * 3072], w2 = wp[(size_t)(kk + 2) * 3072], w3 = wp[(size_t)(kk + 3) * 3072];
; #pragma unroll
;                 for (int v = 0; v < 9; ++v) {
;                     const float4 sv = *(const float4*)(ssc + v * 1024 + kg * 128 + kk);
;                     acc[v] += sv.x * w0 + sv.y * w1 + sv.z * w2 + sv.w * w3;
;                 }
;             }
	ds_read_b128 v[208:211], v81 offset:400
	ds_read_b128 v[212:215], v81 offset:4496
	ds_read_b128 v[216:219], v81 offset:8592
	ds_read_b128 v[220:223], v81 offset:12688
	ds_read_b128 v[224:227], v81 offset:16784
	ds_read_b128 v[228:231], v81 offset:20880
	ds_read_b128 v[236:239], v81 offset:24976
	ds_read_b128 v[240:243], v81 offset:29072
	ds_read_b128 v[244:247], v81 offset:33168
	s_waitcnt lgkmcnt(9)
	v_fma_f32 v104, v4, v174, v104
	v_fma_f32 v105, v8, v174, v105
	v_fma_f32 v106, v12, v174, v106
	v_fma_f32 v107, v16, v174, v107
	v_fma_f32 v108, v20, v174, v108
	v_fma_f32 v109, v24, v174, v109
	v_fma_f32 v110, v28, v174, v110
	v_fma_f32 v111, v32, v174, v111
	v_fma_f32 v83, v36, v174, v83
	v_fma_f32 v104, v5, v175, v104
	v_fma_f32 v105, v9, v175, v105
	v_fma_f32 v106, v13, v175, v106
	v_fma_f32 v107, v17, v175, v107
	v_fma_f32 v108, v21, v175, v108
	v_fma_f32 v109, v25, v175, v109
	v_fma_f32 v110, v29, v175, v110
	v_fma_f32 v111, v33, v175, v111
	v_fma_f32 v83, v37, v175, v83
	v_fma_f32 v104, v6, v176, v104
	v_fma_f32 v105, v10, v176, v105
	v_fma_f32 v106, v14, v176, v106
	v_fma_f32 v107, v18, v176, v107
	v_fma_f32 v108, v22, v176, v108
	v_fma_f32 v109, v26, v176, v109
	v_fma_f32 v110, v30, v176, v110
	v_fma_f32 v111, v34, v176, v111
	v_fma_f32 v83, v38, v176, v83
	v_fma_f32 v104, v7, v177, v104
	v_fma_f32 v105, v11, v177, v105
	v_fma_f32 v106, v15, v177, v106
	v_fma_f32 v107, v19, v177, v107
	v_fma_f32 v108, v23, v177, v108
	v_fma_f32 v109, v27, v177, v109
	v_fma_f32 v110, v31, v177, v110
	v_fma_f32 v111, v35, v177, v111
	v_fma_f32 v83, v39, v177, v83
	ds_read_b128 v[4:7], v81 offset:416
	ds_read_b128 v[8:11], v81 offset:4512
	ds_read_b128 v[12:15], v81 offset:8608
	ds_read_b128 v[16:19], v81 offset:12704
	ds_read_b128 v[20:23], v81 offset:16800
	ds_read_b128 v[24:27], v81 offset:20896
	ds_read_b128 v[28:31], v81 offset:24992
	ds_read_b128 v[32:35], v81 offset:29088
	ds_read_b128 v[36:39], v81 offset:33184
	s_waitcnt lgkmcnt(9)
	v_fma_f32 v104, v208, v178, v104
	v_fma_f32 v105, v212, v178, v105
	v_fma_f32 v106, v216, v178, v106
	v_fma_f32 v107, v220, v178, v107
	v_fma_f32 v108, v224, v178, v108
	v_fma_f32 v109, v228, v178, v109
	v_fma_f32 v110, v236, v178, v110
	v_fma_f32 v111, v240, v178, v111
	v_fma_f32 v83, v244, v178, v83
	v_fma_f32 v104, v209, v179, v104
	v_fma_f32 v105, v213, v179, v105
	v_fma_f32 v106, v217, v179, v106
	v_fma_f32 v107, v221, v179, v107
	v_fma_f32 v108, v225, v179, v108
	v_fma_f32 v109, v229, v179, v109
	v_fma_f32 v110, v237, v179, v110
	v_fma_f32 v111, v241, v179, v111
	v_fma_f32 v83, v245, v179, v83
	v_fma_f32 v104, v210, v180, v104
	v_fma_f32 v105, v214, v180, v105
	v_fma_f32 v106, v218, v180, v106
	v_fma_f32 v107, v222, v180, v107
	v_fma_f32 v108, v226, v180, v108
	v_fma_f32 v109, v230, v180, v109
	v_fma_f32 v110, v238, v180, v110
	v_fma_f32 v111, v242, v180, v111
	v_fma_f32 v83, v246, v180, v83
	v_fma_f32 v104, v211, v181, v104
	v_fma_f32 v105, v215, v181, v105
	v_fma_f32 v106, v219, v181, v106
	v_fma_f32 v107, v223, v181, v107
	v_fma_f32 v108, v227, v181, v108
	v_fma_f32 v109, v231, v181, v109
	v_fma_f32 v110, v239, v181, v110
	v_fma_f32 v111, v243, v181, v111
	v_fma_f32 v83, v247, v181, v83
	ds_read_b128 v[208:211], v81 offset:432
	ds_read_b128 v[212:215], v81 offset:4528
	ds_read_b128 v[216:219], v81 offset:8624
	ds_read_b128 v[220:223], v81 offset:12720
	ds_read_b128 v[224:227], v81 offset:16816
	ds_read_b128 v[228:231], v81 offset:20912
	ds_read_b128 v[236:239], v81 offset:25008
	ds_read_b128 v[240:243], v81 offset:29104
	ds_read_b128 v[244:247], v81 offset:33200
	s_waitcnt lgkmcnt(9)
	v_fma_f32 v104, v4, v182, v104
	v_fma_f32 v105, v8, v182, v105
	v_fma_f32 v106, v12, v182, v106
	v_fma_f32 v107, v16, v182, v107
	v_fma_f32 v108, v20, v182, v108
	v_fma_f32 v109, v24, v182, v109
	v_fma_f32 v110, v28, v182, v110
	v_fma_f32 v111, v32, v182, v111
	v_fma_f32 v83, v36, v182, v83
	v_fma_f32 v104, v5, v183, v104
	v_fma_f32 v105, v9, v183, v105
	v_fma_f32 v106, v13, v183, v106
	v_fma_f32 v107, v17, v183, v107
	v_fma_f32 v108, v21, v183, v108
	v_fma_f32 v109, v25, v183, v109
	v_fma_f32 v110, v29, v183, v110
	v_fma_f32 v111, v33, v183, v111
	v_fma_f32 v83, v37, v183, v83
	v_fma_f32 v104, v6, v184, v104
	v_fma_f32 v105, v10, v184, v105
	v_fma_f32 v106, v14, v184, v106
	v_fma_f32 v107, v18, v184, v107
	v_fma_f32 v108, v22, v184, v108
	v_fma_f32 v109, v26, v184, v109
	v_fma_f32 v110, v30, v184, v110
	v_fma_f32 v111, v34, v184, v111
	v_fma_f32 v83, v38, v184, v83
	v_fma_f32 v104, v7, v185, v104
	v_fma_f32 v105, v11, v185, v105
	v_fma_f32 v106, v15, v185, v106
	v_fma_f32 v107, v19, v185, v107
	v_fma_f32 v108, v23, v185, v108
	v_fma_f32 v109, v27, v185, v109
	v_fma_f32 v110, v31, v185, v110
	v_fma_f32 v111, v35, v185, v111
	v_fma_f32 v83, v39, v185, v83
	ds_read_b128 v[4:7], v81 offset:448
	ds_read_b128 v[8:11], v81 offset:4544
	ds_read_b128 v[12:15], v81 offset:8640
	ds_read_b128 v[16:19], v81 offset:12736
	ds_read_b128 v[20:23], v81 offset:16832
	ds_read_b128 v[24:27], v81 offset:20928
	ds_read_b128 v[28:31], v81 offset:25024
	ds_read_b128 v[32:35], v81 offset:29120
	ds_read_b128 v[36:39], v81 offset:33216
	s_waitcnt lgkmcnt(9)
; __device__ __forceinline__ void phase0(const Params& p, unsigned char* smem) {
;     ...
;             for (int kk = 0; kk < 128; kk += 4) {
;                 const float w0 = wp[(size_t)(kk + 0) * 3072], w1 = wp[(size_t)(kk + 1) * 3072], w2 = wp[(size_t)(kk + 2) * 3072], w3 = wp[(size_t)(kk + 3) * 3072];
; #pragma unroll
;                 for (int v = 0; v < 9; ++v) {
;                     const float4 sv = *(const float4*)(ssc + v * 1024 + kg * 128 + kk);
;                     acc[v] += sv.x * w0 + sv.y * w1 + sv.z * w2 + sv.w * w3;
;                 }
;             }
	v_fma_f32 v104, v208, v186, v104
	v_fma_f32 v105, v212, v186, v105
	v_fma_f32 v106, v216, v186, v106
	v_fma_f32 v107, v220, v186, v107
	v_fma_f32 v108, v224, v186, v108
	v_fma_f32 v109, v228, v186, v109
	v_fma_f32 v110, v236, v186, v110
	v_fma_f32 v111, v240, v186, v111
	v_fma_f32 v83, v244, v186, v83
	v_fma_f32 v104, v209, v187, v104
	v_fma_f32 v105, v213, v187, v105
	v_fma_f32 v106, v217, v187, v106
	v_fma_f32 v107, v221, v187, v107
	v_fma_f32 v108, v225, v187, v108
	v_fma_f32 v109, v229, v187, v109
	v_fma_f32 v110, v237, v187, v110
	v_fma_f32 v111, v241, v187, v111
	v_fma_f32 v83, v245, v187, v83
	v_fma_f32 v104, v210, v188, v104
	v_fma_f32 v105, v214, v188, v105
	v_fma_f32 v106, v218, v188, v106
	v_fma_f32 v107, v222, v188, v107
	v_fma_f32 v108, v226, v188, v108
	v_fma_f32 v109, v230, v188, v109
	v_fma_f32 v110, v238, v188, v110
	v_fma_f32 v111, v242, v188, v111
	v_fma_f32 v83, v246, v188, v83
	v_fma_f32 v104, v211, v189, v104
	v_fma_f32 v105, v215, v189, v105
	v_fma_f32 v106, v219, v189, v106
	v_fma_f32 v107, v223, v189, v107
	v_fma_f32 v108, v227, v189, v108
	v_fma_f32 v109, v231, v189, v109
	v_fma_f32 v110, v239, v189, v110
	v_fma_f32 v111, v243, v189, v111
	v_fma_f32 v83, v247, v189, v83
	ds_read_b128 v[208:211], v81 offset:464
	ds_read_b128 v[212:215], v81 offset:4560
	ds_read_b128 v[216:219], v81 offset:8656
	ds_read_b128 v[220:223], v81 offset:12752
	ds_read_b128 v[224:227], v81 offset:16848
	ds_read_b128 v[228:231], v81 offset:20944
	ds_read_b128 v[236:239], v81 offset:25040
	ds_read_b128 v[240:243], v81 offset:29136
	ds_read_b128 v[244:247], v81 offset:33232
	s_waitcnt lgkmcnt(9)
	v_fma_f32 v104, v4, v190, v104
	v_fma_f32 v105, v8, v190, v105
	v_fma_f32 v106, v12, v190, v106
	v_fma_f32 v107, v16, v190, v107
	v_fma_f32 v108, v20, v190, v108
	v_fma_f32 v109, v24, v190, v109
	v_fma_f32 v110, v28, v190, v110
	v_fma_f32 v111, v32, v190, v111
	v_fma_f32 v83, v36, v190, v83
	v_fma_f32 v104, v5, v191, v104
	v_fma_f32 v105, v9, v191, v105
	v_fma_f32 v106, v13, v191, v106
	v_fma_f32 v107, v17, v191, v107
	v_fma_f32 v108, v21, v191, v108
	v_fma_f32 v109, v25, v191, v109
	v_fma_f32 v110, v29, v191, v110
	v_fma_f32 v111, v33, v191, v111
	v_fma_f32 v83, v37, v191, v83
	v_fma_f32 v104, v6, v192, v104
	v_fma_f32 v105, v10, v192, v105
	v_fma_f32 v106, v14, v192, v106
	v_fma_f32 v107, v18, v192, v107
	v_fma_f32 v108, v22, v192, v108
	v_fma_f32 v109, v26, v192, v109
	v_fma_f32 v110, v30, v192, v110
	v_fma_f32 v111, v34, v192, v111
	v_fma_f32 v83, v38, v192, v83
	v_fma_f32 v104, v7, v193, v104
	v_fma_f32 v105, v11, v193, v105
	v_fma_f32 v106, v15, v193, v106
	v_fma_f32 v107, v19, v193, v107
	v_fma_f32 v108, v23, v193, v108
	v_fma_f32 v109, v27, v193, v109
	v_fma_f32 v110, v31, v193, v110
	v_fma_f32 v111, v35, v193, v111
	v_fma_f32 v83, v39, v193, v83
	ds_read_b128 v[4:7], v81 offset:480
	ds_read_b128 v[8:11], v81 offset:4576
	ds_read_b128 v[12:15], v81 offset:8672
	ds_read_b128 v[16:19], v81 offset:12768
	ds_read_b128 v[20:23], v81 offset:16864
	ds_read_b128 v[24:27], v81 offset:20960
	ds_read_b128 v[28:31], v81 offset:25056
	ds_read_b128 v[32:35], v81 offset:29152
	ds_read_b128 v[36:39], v81 offset:33248
	s_waitcnt lgkmcnt(9)
; __device__ __forceinline__ void phase0(const Params& p, unsigned char* smem) {
;     ...
;             for (int kk = 0; kk < 128; kk += 4) {
;                 const float w0 = wp[(size_t)(kk + 0) * 3072], w1 = wp[(size_t)(kk + 1) * 3072], w2 = wp[(size_t)(kk + 2) * 3072], w3 = wp[(size_t)(kk + 3) * 3072];
; #pragma unroll
;                 for (int v = 0; v < 9; ++v) {
;                     const float4 sv = *(const float4*)(ssc + v * 1024 + kg * 128 + kk);
;                     acc[v] += sv.x * w0 + sv.y * w1 + sv.z * w2 + sv.w * w3;
;                 }
;             }
; #pragma unroll
;             for (int v = 0; v < 9; ++v) red[(kg * 9 + v) * 64 + col] = acc[v];
;             __syncthreads();
;             for (int idx = tid; idx < 9 * 64; idx += NTHR) {
	v_fma_f32 v104, v208, v194, v104
	v_fma_f32 v105, v212, v194, v105
	v_fma_f32 v106, v216, v194, v106
	v_fma_f32 v107, v220, v194, v107
	v_fma_f32 v108, v224, v194, v108
	v_fma_f32 v109, v228, v194, v109
	v_fma_f32 v110, v236, v194, v110
	v_fma_f32 v111, v240, v194, v111
	v_fma_f32 v83, v244, v194, v83
	v_fma_f32 v104, v209, v195, v104
	v_fma_f32 v105, v213, v195, v105
	v_fma_f32 v106, v217, v195, v106
	v_fma_f32 v107, v221, v195, v107
	v_fma_f32 v108, v225, v195, v108
	v_fma_f32 v109, v229, v195, v109
	v_fma_f32 v110, v237, v195, v110
	v_fma_f32 v111, v241, v195, v111
	v_fma_f32 v83, v245, v195, v83
	v_fma_f32 v104, v210, v196, v104
	v_fma_f32 v105, v214, v196, v105
	v_fma_f32 v106, v218, v196, v106
	v_fma_f32 v107, v222, v196, v107
	v_fma_f32 v108, v226, v196, v108
	v_fma_f32 v109, v230, v196, v109
	v_fma_f32 v110, v238, v196, v110
	v_fma_f32 v111, v242, v196, v111
	v_fma_f32 v83, v246, v196, v83
	v_fma_f32 v104, v211, v197, v104
	v_fma_f32 v105, v215, v197, v105
	v_fma_f32 v106, v219, v197, v106
	v_fma_f32 v107, v223, v197, v107
	v_fma_f32 v108, v227, v197, v108
	v_fma_f32 v109, v231, v197, v109
	v_fma_f32 v110, v239, v197, v110
	v_fma_f32 v111, v243, v197, v111
	v_fma_f32 v83, v247, v197, v83
	ds_read_b128 v[208:211], v81 offset:496
	ds_read_b128 v[212:215], v81 offset:4592
	ds_read_b128 v[216:219], v81 offset:8688
	ds_read_b128 v[220:223], v81 offset:12784
	ds_read_b128 v[224:227], v81 offset:16880
	ds_read_b128 v[228:231], v81 offset:20976
	ds_read_b128 v[236:239], v81 offset:25072
	ds_read_b128 v[240:243], v81 offset:29168
	ds_read_b128 v[244:247], v81 offset:33264
	s_waitcnt lgkmcnt(9)
	v_fma_f32 v104, v4, v198, v104
	v_fma_f32 v105, v8, v198, v105
	v_fma_f32 v106, v12, v198, v106
	v_fma_f32 v107, v16, v198, v107
	v_fma_f32 v108, v20, v198, v108
	v_fma_f32 v109, v24, v198, v109
	v_fma_f32 v110, v28, v198, v110
	v_fma_f32 v111, v32, v198, v111
	v_fma_f32 v83, v36, v198, v83
	v_fma_f32 v104, v5, v199, v104
	v_fma_f32 v105, v9, v199, v105
	v_fma_f32 v106, v13, v199, v106
	v_fma_f32 v107, v17, v199, v107
	v_fma_f32 v108, v21, v199, v108
	v_fma_f32 v109, v25, v199, v109
	v_fma_f32 v110, v29, v199, v110
	v_fma_f32 v111, v33, v199, v111
	v_fma_f32 v83, v37, v199, v83
	v_fma_f32 v104, v6, v200, v104
	v_fma_f32 v105, v10, v200, v105
	v_fma_f32 v106, v14, v200, v106
	v_fma_f32 v107, v18, v200, v107
	v_fma_f32 v108, v22, v200, v108
	v_fma_f32 v109, v26, v200, v109
	v_fma_f32 v110, v30, v200, v110
	v_fma_f32 v111, v34, v200, v111
	v_fma_f32 v83, v38, v200, v83
	v_fma_f32 v104, v7, v201, v104
	v_fma_f32 v105, v11, v201, v105
	v_fma_f32 v106, v15, v201, v106
	v_fma_f32 v107, v19, v201, v107
	v_fma_f32 v108, v23, v201, v108
	v_fma_f32 v109, v27, v201, v109
	v_fma_f32 v110, v31, v201, v110
	v_fma_f32 v111, v35, v201, v111
	v_fma_f32 v83, v39, v201, v83
	s_waitcnt lgkmcnt(0)
	v_fma_f32 v104, v208, v202, v104
	v_fma_f32 v105, v212, v202, v105
	v_fma_f32 v106, v216, v202, v106
	v_fma_f32 v107, v220, v202, v107
	v_fma_f32 v108, v224, v202, v108
	v_fma_f32 v109, v228, v202, v109
	v_fma_f32 v110, v236, v202, v110
	v_fma_f32 v111, v240, v202, v111
	v_fma_f32 v83, v244, v202, v83
	v_fma_f32 v104, v209, v203, v104
	v_fma_f32 v105, v213, v203, v105
	v_fma_f32 v106, v217, v203, v106
	v_fma_f32 v107, v221, v203, v107
	v_fma_f32 v108, v225, v203, v108
	v_fma_f32 v109, v229, v203, v109
	v_fma_f32 v110, v237, v203, v110
	v_fma_f32 v111, v241, v203, v111
	v_fma_f32 v83, v245, v203, v83
	v_fma_f32 v104, v210, v204, v104
	v_fma_f32 v105, v214, v204, v105
	v_fma_f32 v106, v218, v204, v106
	v_fma_f32 v107, v222, v204, v107
	v_fma_f32 v108, v226, v204, v108
	v_fma_f32 v109, v230, v204, v109
	v_fma_f32 v110, v238, v204, v110
	v_fma_f32 v111, v242, v204, v111
	v_fma_f32 v83, v246, v204, v83
	v_fma_f32 v104, v211, v205, v104
	v_fma_f32 v105, v215, v205, v105
	v_fma_f32 v106, v219, v205, v106
	v_fma_f32 v107, v223, v205, v107
	v_fma_f32 v108, v227, v205, v108
	v_fma_f32 v109, v231, v205, v109
	v_fma_f32 v110, v239, v205, v110
	v_fma_f32 v111, v243, v205, v111
	v_fma_f32 v83, v247, v205, v83
	ds_write2st64_b32 v126, v104, v105 offset0:144 offset1:145
	ds_write2st64_b32 v126, v106, v107 offset0:146 offset1:147
	ds_write2st64_b32 v126, v108, v109 offset0:148 offset1:149
	ds_write2st64_b32 v126, v110, v111 offset0:150 offset1:151
	ds_write_b32 v126, v83 offset:38912
	s_waitcnt lgkmcnt(0)
	s_barrier
	s_and_saveexec_b64 s[20:21], s[10:11]
	s_cbranch_execz .LBB0_4
	s_load_dwordx16 s[76:91], s[0:1], 0x0
	s_mul_i32 s22, s26, 0xc00
	s_add_i32 s42, s22, s24
	v_or_b32_e32 v2, s42, v118
	v_ashrrev_i32_e32 v3, 31, v2
	s_mul_hi_i32 s23, s26, 9
	s_mul_i32 s22, s26, 9
	s_waitcnt lgkmcnt(0)
	v_lshl_add_u64 v[2:3], v[2:3], 2, s[88:89]
	v_lshl_add_u64 v[4:5], s[24:25], 2, v[76:77]
	s_mov_b64 s[24:25], 0
	v_mov_b32_e32 v6, v70
